# C item epilogue: permlane32_swap pairs so each lane stores 16 B (8 dwordx4 instead of 16 dwordx2 stores per lane)
# speedup vs baseline: 1.0082x; 1.0082x over previous
.LBB0_779:
	v_mov_b32_e32 v43, v0
	s_ashr_i32 s5, s3, 31
	v_ashrrev_i32_e32 v44, 7, v43
	s_waitcnt vmcnt(2)
	v_add_u32_e32 v164, s2, v44
	v_ashrrev_i32_e32 v165, 31, v164
	v_and_b32_e32 v168, 31, v43
	s_waitcnt vmcnt(0)
	v_lshlrev_b64 v[2:3], 15, v[164:165]
	v_bfe_u32 v169, v43, 5, 1
	v_lshl_add_u64 v[2:3], s[56:57], 0, v[2:3]
	v_lshlrev_b32_e32 v154, 8, v168
	v_lshl_add_u64 v[2:3], v[2:3], 0, v[154:155]
	v_lshlrev_b32_e32 v154, 4, v169
	v_lshl_add_u64 v[18:19], v[2:3], 0, v[154:155]
	v_add_co_u32_e32 v20, vcc, s14, v18
	v_ashrrev_i32_e32 v45, 2, v43
	s_nop 0
	v_addc_co_u32_e32 v21, vcc, 0, v19, vcc
	v_add_co_u32_e32 v22, vcc, s17, v18
	global_load_dwordx4 v[2:5], v[18:19], off
	global_load_dwordx4 v[6:9], v[20:21], off
	v_addc_co_u32_e32 v23, vcc, 0, v19, vcc
	v_add_co_u32_e32 v24, vcc, s30, v18
	global_load_dwordx4 v[10:13], v[22:23], off
	s_nop 0
	v_addc_co_u32_e32 v25, vcc, 0, v19, vcc
	global_load_dwordx4 v[14:17], v[24:25], off
	global_load_dwordx4 v[138:141], v[18:19], off offset:32
	global_load_dwordx4 v[142:145], v[20:21], off offset:32
	global_load_dwordx4 v[146:149], v[22:23], off offset:32
	global_load_dwordx4 v[150:153], v[24:25], off offset:32
	global_load_dwordx4 v[126:129], v[20:21], off offset:64
	global_load_dwordx4 v[130:133], v[22:23], off offset:64
	global_load_dwordx4 v[134:137], v[24:25], off offset:64
	global_load_dwordx4 v[114:117], v[20:21], off offset:96
	global_load_dwordx4 v[118:121], v[22:23], off offset:96
	global_load_dwordx4 v[122:125], v[24:25], off offset:96
	global_load_dwordx4 v[106:109], v[22:23], off offset:128
	global_load_dwordx4 v[110:113], v[24:25], off offset:128
	global_load_dwordx4 v[98:101], v[22:23], off offset:160
	global_load_dwordx4 v[102:105], v[24:25], off offset:160
	global_load_dwordx4 v[94:97], v[24:25], off offset:192
	global_load_dwordx4 v[90:93], v[24:25], off offset:224
	v_add_u32_e32 v18, s3, v45
	v_ashrrev_i32_e32 v19, 31, v18
	v_lshlrev_b32_e32 v20, 6, v43
	v_lshlrev_b64 v[18:19], 12, v[18:19]
	v_and_b32_e32 v46, 0xc0, v20
	v_lshl_add_u64 v[18:19], s[60:61], 0, v[18:19]
	v_lshlrev_b32_e32 v20, 1, v46
	v_mov_b32_e32 v21, v155
	v_lshl_add_u64 v[34:35], v[18:19], 0, v[20:21]
	global_load_dwordx4 v[18:21], v[34:35], off offset:3632
	global_load_dwordx4 v[22:25], v[34:35], off offset:3616
	global_load_dwordx4 v[26:29], v[34:35], off offset:3600
	global_load_dwordx4 v[30:33], v[34:35], off offset:3584
	global_load_dwordx4 v[36:39], v[34:35], off offset:3680
	global_load_dwordx4 v[202:205], v[34:35], off offset:3664
	global_load_dwordx4 v[48:51], v[34:35], off offset:3648
	global_load_dwordx4 v[206:209], v[34:35], off offset:3696
	v_and_b32_e32 v215, 31, v0
	v_add_u32_e32 v215, s3, v215
	v_lshlrev_b32_e32 v215, 12, v215
	v_and_b32_e32 v245, 0x1c0, v0
	v_add_u32_e32 v215, v215, v245
	v_bfe_u32 v245, v0, 5, 1
	v_lshl_add_u32 v215, v245, 3, v215
	global_load_dwordx2 v[216:217], v215, s[60:61] offset:3072
	global_load_dwordx2 v[218:219], v215, s[60:61] offset:3088
	global_load_dwordx2 v[220:221], v215, s[60:61] offset:3104
	global_load_dwordx2 v[222:223], v215, s[60:61] offset:3120
	s_add_u32 s98, s60, 0x20000
	s_addc_u32 s99, s61, 0
	global_load_dwordx2 v[224:225], v215, s[98:99] offset:3072
	global_load_dwordx2 v[226:227], v215, s[98:99] offset:3088
	global_load_dwordx2 v[228:229], v215, s[98:99] offset:3104
	global_load_dwordx2 v[230:231], v215, s[98:99] offset:3120
	s_add_u32 s100, s60, 0x40000
	s_addc_u32 s101, s61, 0
	global_load_dwordx2 v[232:233], v215, s[100:101] offset:3072
	global_load_dwordx2 v[234:235], v215, s[100:101] offset:3088
	global_load_dwordx2 v[236:237], v215, s[100:101] offset:3104
	global_load_dwordx2 v[238:239], v215, s[100:101] offset:3120
	s_add_u32 s98, s60, 0x60000
	s_addc_u32 s99, s61, 0
	global_load_dwordx2 v[240:241], v215, s[98:99] offset:3072
	global_load_dwordx2 v[246:247], v215, s[98:99] offset:3088
	global_load_dwordx2 v[252:253], v215, s[98:99] offset:3104
	global_load_dwordx2 v[254:255], v215, s[98:99] offset:3120
	v_lshrrev_b32_e32 v42, 5, v43
	s_add_i32 s4, s4, s46
	s_waitcnt vmcnt(23)
	v_lshlrev_b32_e32 v178, 16, v18
	s_waitcnt vmcnt(22)
	v_lshlrev_b32_e32 v186, 16, v22
	s_waitcnt vmcnt(21)
	v_lshlrev_b32_e32 v194, 16, v26
	s_waitcnt vmcnt(20)
	v_lshlrev_b32_e32 v200, 16, v30
	v_and_b32_e32 v199, 0xffff0000, v30
	v_add_f32_e32 v30, 0, v200
	v_lshlrev_b32_e32 v198, 16, v31
	v_add_f32_e32 v30, v30, v199
	v_and_b32_e32 v197, 0xffff0000, v31
	v_mul_f32_e32 v31, v199, v199
	v_add_f32_e32 v30, v30, v198
	v_lshlrev_b32_e32 v196, 16, v32
	v_fmac_f32_e32 v31, v200, v200
	v_add_f32_e32 v30, v30, v197
	v_and_b32_e32 v195, 0xffff0000, v32
	v_fmac_f32_e32 v31, v198, v198
	v_add_f32_e32 v30, v30, v196
	v_lshlrev_b32_e32 v193, 16, v33
	v_fmac_f32_e32 v31, v197, v197
	v_add_f32_e32 v30, v30, v195
	v_and_b32_e32 v191, 0xffff0000, v33
	v_fmac_f32_e32 v31, v196, v196
	v_add_f32_e32 v30, v30, v193
	v_fmac_f32_e32 v31, v195, v195
	v_add_f32_e32 v30, v30, v191
	v_fmac_f32_e32 v31, v193, v193
	v_and_b32_e32 v192, 0xffff0000, v26
	v_add_f32_e32 v26, v30, v194
	v_fmac_f32_e32 v31, v191, v191
	v_lshlrev_b32_e32 v190, 16, v27
	v_add_f32_e32 v26, v26, v192
	v_and_b32_e32 v189, 0xffff0000, v27
	v_fmac_f32_e32 v31, v194, v194
	v_add_f32_e32 v26, v26, v190
	v_lshlrev_b32_e32 v188, 16, v28
	v_fmac_f32_e32 v31, v192, v192
	v_add_f32_e32 v26, v26, v189
	v_and_b32_e32 v187, 0xffff0000, v28
	v_fmac_f32_e32 v31, v190, v190
	v_add_f32_e32 v26, v26, v188
	v_lshlrev_b32_e32 v184, 16, v29
	v_fmac_f32_e32 v31, v189, v189
	v_add_f32_e32 v26, v26, v187
	v_and_b32_e32 v182, 0xffff0000, v29
	v_fmac_f32_e32 v31, v188, v188
	v_add_f32_e32 v26, v26, v184
	v_fmac_f32_e32 v31, v187, v187
	v_add_f32_e32 v26, v26, v182
	v_fmac_f32_e32 v31, v184, v184
	v_and_b32_e32 v185, 0xffff0000, v22
	v_add_f32_e32 v22, v26, v186
	v_fmac_f32_e32 v31, v182, v182
	v_lshlrev_b32_e32 v183, 16, v23
	v_add_f32_e32 v22, v22, v185
	v_and_b32_e32 v179, 0xffff0000, v23
	v_fmac_f32_e32 v31, v186, v186
	v_add_f32_e32 v22, v22, v183
	v_lshlrev_b32_e32 v177, 16, v24
	v_fmac_f32_e32 v31, v185, v185
	v_add_f32_e32 v22, v22, v179
	v_and_b32_e32 v175, 0xffff0000, v24
	v_fmac_f32_e32 v31, v183, v183
	v_add_f32_e32 v22, v22, v177
	v_lshlrev_b32_e32 v173, 16, v25
	v_fmac_f32_e32 v31, v179, v179
	v_add_f32_e32 v22, v22, v175
	v_and_b32_e32 v171, 0xffff0000, v25
	v_fmac_f32_e32 v31, v177, v177
	v_add_f32_e32 v22, v22, v173
	v_fmac_f32_e32 v31, v175, v175
	v_add_f32_e32 v22, v22, v171
	v_fmac_f32_e32 v31, v173, v173
	v_and_b32_e32 v176, 0xffff0000, v18
	v_add_f32_e32 v18, v22, v178
	v_fmac_f32_e32 v31, v171, v171
	v_lshlrev_b32_e32 v174, 16, v19
	v_add_f32_e32 v18, v18, v176
	v_and_b32_e32 v172, 0xffff0000, v19
	v_fmac_f32_e32 v31, v178, v178
	v_add_f32_e32 v18, v18, v174
	v_lshlrev_b32_e32 v167, 16, v20
	v_fmac_f32_e32 v31, v176, v176
	v_add_f32_e32 v18, v18, v172
	v_and_b32_e32 v165, 0xffff0000, v20
	v_fmac_f32_e32 v31, v174, v174
	v_add_f32_e32 v18, v18, v167
	v_lshlrev_b32_e32 v64, 16, v21
	v_fmac_f32_e32 v31, v172, v172
	v_add_f32_e32 v18, v18, v165
	v_and_b32_e32 v62, 0xffff0000, v21
	v_fmac_f32_e32 v31, v167, v167
	v_add_f32_e32 v18, v18, v64
	v_fmac_f32_e32 v31, v165, v165
	v_add_f32_e32 v18, v18, v62
	s_waitcnt vmcnt(17)
	v_lshlrev_b32_e32 v170, 16, v48
	v_fmac_f32_e32 v31, v64, v64
	v_and_b32_e32 v166, 0xffff0000, v48
	v_add_f32_e32 v18, v18, v170
	v_fmac_f32_e32 v31, v62, v62
	v_lshlrev_b32_e32 v65, 16, v49
	v_add_f32_e32 v18, v18, v166
	v_and_b32_e32 v63, 0xffff0000, v49
	v_fmac_f32_e32 v31, v170, v170
	v_add_f32_e32 v18, v18, v65
	v_lshlrev_b32_e32 v60, 16, v50
	v_fmac_f32_e32 v31, v166, v166
	v_add_f32_e32 v18, v18, v63
	v_and_b32_e32 v59, 0xffff0000, v50
	v_fmac_f32_e32 v31, v65, v65
	v_add_f32_e32 v18, v18, v60
	v_lshlrev_b32_e32 v57, 16, v51
	v_fmac_f32_e32 v31, v63, v63
	v_add_f32_e32 v18, v18, v59
	v_and_b32_e32 v55, 0xffff0000, v51
	v_fmac_f32_e32 v31, v60, v60
	v_add_f32_e32 v18, v18, v57
	v_fmac_f32_e32 v31, v59, v59
	v_add_f32_e32 v18, v18, v55
	v_lshlrev_b32_e32 v61, 16, v202
	v_fmac_f32_e32 v31, v57, v57
	v_and_b32_e32 v58, 0xffff0000, v202
	v_add_f32_e32 v18, v18, v61
	v_fmac_f32_e32 v31, v55, v55
	v_lshlrev_b32_e32 v56, 16, v203
	v_add_f32_e32 v18, v18, v58
	v_and_b32_e32 v54, 0xffff0000, v203
	v_fmac_f32_e32 v31, v61, v61
	v_add_f32_e32 v18, v18, v56
	v_lshlrev_b32_e32 v53, 16, v204
	v_fmac_f32_e32 v31, v58, v58
	v_add_f32_e32 v18, v18, v54
	v_and_b32_e32 v51, 0xffff0000, v204
	v_fmac_f32_e32 v31, v56, v56
	v_add_f32_e32 v18, v18, v53
	v_lshlrev_b32_e32 v49, 16, v205
	v_fmac_f32_e32 v31, v54, v54
	v_add_f32_e32 v18, v18, v51
	v_and_b32_e32 v47, 0xffff0000, v205
	v_fmac_f32_e32 v31, v53, v53
	v_add_f32_e32 v18, v18, v49
	v_fmac_f32_e32 v31, v51, v51
	v_add_f32_e32 v18, v18, v47
	v_lshlrev_b32_e32 v52, 16, v36
	v_fmac_f32_e32 v31, v49, v49
	v_and_b32_e32 v50, 0xffff0000, v36
	v_add_f32_e32 v18, v18, v52
	v_fmac_f32_e32 v31, v47, v47
	v_lshlrev_b32_e32 v48, 16, v37
	v_add_f32_e32 v18, v18, v50
	v_fmac_f32_e32 v31, v52, v52
	v_add_f32_e32 v18, v18, v48
	v_and_b32_e32 v37, 0xffff0000, v37
	v_fmac_f32_e32 v31, v50, v50
	v_lshlrev_b32_e32 v34, 16, v38
	v_mov_b32_e32 v35, v37
	v_add_f32_e32 v20, v18, v37
	v_fmac_f32_e32 v31, v48, v48
	v_and_b32_e32 v24, 0xffff0000, v38
	v_pk_mul_f32 v[18:19], v[34:35], v[34:35]
	v_add_f32_e32 v20, v20, v34
	v_lshlrev_b32_e32 v25, 16, v39
	v_add_f32_e32 v19, v19, v31
	v_add_f32_e32 v20, v20, v24
	v_add_f32_e32 v21, v18, v19
	v_pk_mul_f32 v[18:19], v[24:25], v[24:25]
	v_add_f32_e32 v20, v20, v25
	v_and_b32_e32 v33, 0xffff0000, v39
	v_add_f32_e32 v18, v18, v21
	s_waitcnt vmcnt(16)
	v_lshlrev_b32_e32 v28, 16, v206
	v_mov_b32_e32 v29, v33
	v_add_f32_e32 v20, v20, v33
	v_add_f32_e32 v21, v19, v18
	v_and_b32_e32 v22, 0xffff0000, v206
	v_pk_mul_f32 v[18:19], v[28:29], v[28:29]
	v_add_f32_e32 v20, v20, v28
	v_lshlrev_b32_e32 v23, 16, v207
	v_add_f32_e32 v19, v19, v21
	v_add_f32_e32 v20, v20, v22
	v_add_f32_e32 v21, v18, v19
	v_pk_mul_f32 v[18:19], v[22:23], v[22:23]
	v_add_f32_e32 v29, v20, v23
	v_and_b32_e32 v31, 0xffff0000, v207
	v_add_f32_e32 v18, v18, v21
	v_lshlrev_b32_e32 v26, 16, v208
	v_mov_b32_e32 v27, v31
	v_add_f32_e32 v29, v29, v31
	v_and_b32_e32 v36, s0, v38
	v_add_f32_e32 v18, v19, v18
	v_and_b32_e32 v20, 0xffff0000, v208
	v_pk_mul_f32 v[38:39], v[26:27], v[26:27]
	v_add_f32_e32 v27, v29, v26
	v_lshlrev_b32_e32 v21, 16, v209
	v_add_f32_e32 v18, v39, v18
	v_add_f32_e32 v27, v27, v20
	v_and_b32_e32 v29, 64, v181
	v_add_f32_e32 v18, v38, v18
	v_pk_mul_f32 v[40:41], v[20:21], v[20:21]
	v_add_f32_e32 v39, v27, v21
	v_xor_b32_e32 v27, 1, v181
	v_add_u32_e32 v29, 64, v29
	v_and_b32_e32 v19, 0xffff0000, v209
	v_add_f32_e32 v18, v40, v18
	v_cmp_lt_i32_e32 vcc, v27, v29
	v_add_f32_e32 v18, v41, v18
	v_mul_f32_e32 v38, v19, v19
	v_cndmask_b32_e32 v27, v181, v27, vcc
	v_lshlrev_b32_e32 v27, 2, v27
	v_pk_add_f32 v[38:39], v[38:39], v[18:19]
	ds_bpermute_b32 v41, v27, v39
	ds_bpermute_b32 v40, v27, v38
	v_xor_b32_e32 v35, 2, v181
	v_cmp_lt_i32_e32 vcc, v35, v29
	v_and_b32_e32 v30, s0, v206
	v_mov_b32_e32 v32, v36
	v_cndmask_b32_e32 v29, v181, v35, vcc
	v_lshlrev_b32_e32 v29, 2, v29
	s_waitcnt lgkmcnt(0)
	v_pk_add_f32 v[38:39], v[38:39], v[40:41]
	ds_bpermute_b32 v41, v29, v39
	ds_bpermute_b32 v40, v29, v38
	s_waitcnt lgkmcnt(0)
	v_pk_add_f32 v[40:41], v[38:39], v[40:41]
	s_nop 0
	v_pk_mul_f32 v[38:39], v[40:41], s[22:23] op_sel_hi:[1,0]
	v_pk_fma_f32 v[36:37], v[40:41], s[22:23], v[36:37] op_sel_hi:[1,0,1] neg_lo:[1,0,0] neg_hi:[1,0,0]
	v_fma_f32 v18, -v39, v39, v38
	v_max_f32_e32 v18, 0, v18
	v_add_f32_e32 v18, 0x358637bd, v18
	v_cmp_gt_f32_e32 vcc, s33, v18
	v_mul_f32_e32 v27, 0x4b800000, v18
	v_sub_f32_e32 v29, v200, v39
	v_cndmask_b32_e32 v18, v18, v27, vcc
	v_rsq_f32_e32 v18, v18
	v_sub_f32_e32 v19, v19, v39
	v_mul_f32_e32 v27, 0x45800000, v18
	v_cndmask_b32_e32 v18, v18, v27, vcc
	v_mul_f32_e32 v29, v29, v18
	v_lshlrev_b32_e32 v27, 1, v45
	v_bfe_u32 v35, v29, 16, 1
	v_ashrrev_i32_e32 v45, 1, v43
	v_and_b32_e32 v27, 14, v27
	v_add3_u32 v29, v29, v35, s15
	v_lshl_add_u32 v35, v46, 8, 32
	v_and_b32_e32 v46, -16, v45
	v_add3_u32 v200, v35, v46, v27
	ds_write_b16_d16_hi v200, v29 offset:55296
	v_mul_f32_e64 v215, -v39, v18
	v_fma_f32 v29, v199, v18, v215
	v_cvt_pk_bf16_f32 v29, v29, v29
	v_bitop3_b32 v199, v45, 16, -16 bitop3:0x6c
	v_add3_u32 v201, v35, v199, v27
	ds_write_b16 v201, v29 offset:55552
	v_fma_f32 v29, v198, v18, v215
	v_cvt_pk_bf16_f32 v29, v29, v29
	v_bitop3_b32 v198, v45, 32, -16 bitop3:0x6c
	v_add3_u32 v202, v35, v198, v27
	ds_write_b16 v202, v29 offset:55808
	v_fma_f32 v29, v197, v18, v215
	v_cvt_pk_bf16_f32 v29, v29, v29
	v_bitop3_b32 v197, v45, 48, -16 bitop3:0x6c
	v_add3_u32 v203, v35, v197, v27
	ds_write_b16 v203, v29 offset:56064
	v_fma_f32 v29, v196, v18, v215
	v_cvt_pk_bf16_f32 v29, v29, v29
	v_bitop3_b32 v196, v45, 64, -16 bitop3:0x6c
	v_add3_u32 v204, v35, v196, v27
	ds_write_b16 v204, v29 offset:56320
	v_fma_f32 v29, v195, v18, v215
	v_cvt_pk_bf16_f32 v29, v29, v29
	v_bitop3_b32 v195, v45, s34, -16 bitop3:0x6c
	v_add3_u32 v205, v35, v195, v27
	ds_write_b16 v205, v29 offset:56576
	v_fma_f32 v29, v193, v18, v215
	v_cvt_pk_bf16_f32 v29, v29, v29
	v_bitop3_b32 v193, v45, s31, -16 bitop3:0x6c
	v_add3_u32 v206, v35, v193, v27
	ds_write_b16 v206, v29 offset:56832
	v_fma_f32 v29, v191, v18, v215
	v_cvt_pk_bf16_f32 v29, v29, v29
	v_bitop3_b32 v191, v45, s13, -16 bitop3:0x6c
	v_add3_u32 v207, v35, v191, v27
	ds_write_b16 v207, v29 offset:57088
	v_fma_f32 v29, v194, v18, v215
	v_cvt_pk_bf16_f32 v29, v29, v29
	v_bitop3_b32 v194, v45, s12, -16 bitop3:0x6c
	v_add3_u32 v208, v35, v194, v27
	ds_write_b16 v208, v29 offset:57344
	v_fma_f32 v29, v192, v18, v215
	v_cvt_pk_bf16_f32 v29, v29, v29
	v_bitop3_b32 v192, v45, s35, -16 bitop3:0x6c
	v_add3_u32 v209, v35, v192, v27
	ds_write_b16 v209, v29 offset:57600
	v_fma_f32 v29, v190, v18, v215
	v_cvt_pk_bf16_f32 v29, v29, v29
	v_bitop3_b32 v190, v45, s36, -16 bitop3:0x6c
	v_add3_u32 v210, v35, v190, v27
	ds_write_b16 v210, v29 offset:57856
	v_fma_f32 v29, v189, v18, v215
	v_cvt_pk_bf16_f32 v29, v29, v29
	v_bitop3_b32 v189, v45, s37, -16 bitop3:0x6c
	v_add3_u32 v211, v35, v189, v27
	ds_write_b16 v211, v29 offset:58112
	v_fma_f32 v29, v188, v18, v215
	v_cvt_pk_bf16_f32 v29, v29, v29
	v_bitop3_b32 v188, v45, s16, -16 bitop3:0x6c
	v_add3_u32 v212, v35, v188, v27
	ds_write_b16 v212, v29 offset:58368
	v_fma_f32 v29, v187, v18, v215
	v_cvt_pk_bf16_f32 v29, v29, v29
	v_bitop3_b32 v187, v45, s42, -16 bitop3:0x6c
	v_add3_u32 v213, v35, v187, v27
	ds_write_b16 v213, v29 offset:58624
	v_fma_f32 v29, v184, v18, v215
	v_cvt_pk_bf16_f32 v29, v29, v29
	v_bitop3_b32 v184, v45, s43, -16 bitop3:0x6c
	v_add3_u32 v214, v35, v184, v27
	ds_write_b16 v214, v29 offset:58880
	v_sub_f32_e32 v29, v182, v39
	v_mul_f32_e32 v29, v29, v18
	v_bfe_u32 v182, v29, 16, 1
	v_bitop3_b32 v45, v45, s94, -16 bitop3:0x6c
	v_add_u32_e32 v38, 0xd800, v35
	v_add3_u32 v29, v29, v182, s15
	v_add3_u32 v35, v35, v45, v27
	ds_write_b16_d16_hi v35, v29 offset:59136
	v_fma_f32 v29, v186, v18, v215
	v_cvt_pk_bf16_f32 v29, v29, v29
	ds_write_b16 v200, v29 offset:59392
	v_fma_f32 v29, v185, v18, v215
	v_cvt_pk_bf16_f32 v29, v29, v29
	ds_write_b16 v201, v29 offset:59648
	v_fma_f32 v29, v183, v18, v215
	v_cvt_pk_bf16_f32 v29, v29, v29
	ds_write_b16 v202, v29 offset:59904
	v_fma_f32 v29, v179, v18, v215
	v_cvt_pk_bf16_f32 v29, v29, v29
	ds_write_b16 v203, v29 offset:60160
	v_fma_f32 v29, v177, v18, v215
	v_cvt_pk_bf16_f32 v29, v29, v29
	ds_write_b16 v204, v29 offset:60416
	v_fma_f32 v29, v175, v18, v215
	v_cvt_pk_bf16_f32 v29, v29, v29
	ds_write_b16 v205, v29 offset:60672
	v_fma_f32 v29, v173, v18, v215
	v_cvt_pk_bf16_f32 v29, v29, v29
	ds_write_b16 v206, v29 offset:60928
	v_fma_f32 v29, v171, v18, v215
	v_cvt_pk_bf16_f32 v29, v29, v29
	ds_write_b16 v207, v29 offset:61184
	v_fma_f32 v29, v178, v18, v215
	v_cvt_pk_bf16_f32 v29, v29, v29
	ds_write_b16 v208, v29 offset:61440
	v_fma_f32 v29, v176, v18, v215
	v_cvt_pk_bf16_f32 v29, v29, v29
	ds_write_b16 v209, v29 offset:61696
	v_fma_f32 v29, v174, v18, v215
	v_cvt_pk_bf16_f32 v29, v29, v29
	ds_write_b16 v210, v29 offset:61952
	v_fma_f32 v29, v172, v18, v215
	v_cvt_pk_bf16_f32 v29, v29, v29
	ds_write_b16 v211, v29 offset:62208
	v_fma_f32 v29, v167, v18, v215
	v_cvt_pk_bf16_f32 v29, v29, v29
	ds_write_b16 v212, v29 offset:62464
	v_fma_f32 v29, v165, v18, v215
	v_cvt_pk_bf16_f32 v29, v29, v29
	ds_write_b16 v213, v29 offset:62720
	v_fma_f32 v29, v64, v18, v215
	v_cvt_pk_bf16_f32 v29, v29, v29
	ds_write_b16 v214, v29 offset:62976
	v_fma_f32 v29, v62, v18, v215
	v_cvt_pk_bf16_f32 v29, v29, v29
	ds_write_b16 v35, v29 offset:63232
	v_fma_f32 v29, v170, v18, v215
	v_cvt_pk_bf16_f32 v29, v29, v29
	ds_write_b16 v200, v29 offset:63488
	v_fma_f32 v29, v166, v18, v215
	v_cvt_pk_bf16_f32 v29, v29, v29
	ds_write_b16 v201, v29 offset:63744
	v_fma_f32 v29, v65, v18, v215
	v_cvt_pk_bf16_f32 v29, v29, v29
	ds_write_b16 v202, v29 offset:64000
	v_fma_f32 v29, v63, v18, v215
	v_cvt_pk_bf16_f32 v29, v29, v29
	ds_write_b16 v203, v29 offset:64256
	v_fma_f32 v29, v60, v18, v215
	v_cvt_pk_bf16_f32 v29, v29, v29
	ds_write_b16 v204, v29 offset:64512
	v_fma_f32 v29, v59, v18, v215
	v_cvt_pk_bf16_f32 v29, v29, v29
	ds_write_b16 v205, v29 offset:64768
	v_fma_f32 v29, v57, v18, v215
	v_cvt_pk_bf16_f32 v29, v29, v29
	ds_write_b16 v206, v29 offset:65024
	v_fma_f32 v29, v55, v18, v215
	v_cvt_pk_bf16_f32 v29, v29, v29
	ds_write_b16 v207, v29 offset:65280
	v_fma_f32 v29, v61, v18, v215
	v_cvt_pk_bf16_f32 v29, v29, v29
	v_add3_u32 v35, v38, v194, v27
	ds_write_b16 v35, v29 offset:10240
	v_fma_f32 v29, v58, v18, v215
	v_cvt_pk_bf16_f32 v29, v29, v29
	v_add3_u32 v55, v38, v192, v27
	ds_write_b16 v55, v29 offset:10496
	v_fma_f32 v29, v56, v18, v215
	v_cvt_pk_bf16_f32 v29, v29, v29
	v_add3_u32 v56, v38, v190, v27
	ds_write_b16 v56, v29 offset:10752
	v_fma_f32 v29, v54, v18, v215
	v_cvt_pk_bf16_f32 v29, v29, v29
	v_add3_u32 v54, v38, v189, v27
	ds_write_b16 v54, v29 offset:11008
	v_fma_f32 v29, v53, v18, v215
	v_cvt_pk_bf16_f32 v29, v29, v29
	v_add3_u32 v53, v38, v188, v27
	ds_write_b16 v53, v29 offset:11264
	v_fma_f32 v29, v51, v18, v215
	v_cvt_pk_bf16_f32 v29, v29, v29
	v_add3_u32 v51, v38, v187, v27
	ds_write_b16 v51, v29 offset:11520
	v_fma_f32 v29, v49, v18, v215
	v_cvt_pk_bf16_f32 v29, v29, v29
	v_add3_u32 v49, v38, v184, v27
	ds_write_b16 v49, v29 offset:11776
	v_fma_f32 v29, v47, v18, v215
	v_cvt_pk_bf16_f32 v29, v29, v29
	v_add3_u32 v45, v38, v45, v27
	ds_write_b16 v45, v29 offset:12032
	v_fma_f32 v29, v52, v18, v215
	v_cvt_pk_bf16_f32 v29, v29, v29
	v_add3_u32 v46, v38, v46, v27
	ds_write_b16 v46, v29 offset:12288
	v_fma_f32 v29, v50, v18, v215
	v_cvt_pk_bf16_f32 v29, v29, v29
	v_add3_u32 v46, v38, v199, v27
	ds_write_b16 v46, v29 offset:12544
	v_fma_f32 v29, v48, v18, v215
	v_cvt_pk_bf16_f32 v29, v29, v29
	v_add3_u32 v46, v38, v198, v27
	ds_write_b16 v46, v29 offset:12800
	v_mul_f32_e32 v29, v37, v18
	v_bfe_u32 v36, v29, 16, 1
	v_add3_u32 v29, v29, v36, s15
	v_add3_u32 v36, v38, v197, v27
	ds_write_b16_d16_hi v36, v29 offset:13056
	v_fma_f32 v29, v34, v18, v215
	v_cvt_pk_bf16_f32 v29, v29, v29
	v_add3_u32 v34, v38, v196, v27
	ds_write_b16 v34, v29 offset:13312
	v_sub_f32_e32 v29, v24, v39
	v_pk_fma_f32 v[24:25], v[40:41], s[22:23], v[24:25] op_sel_hi:[1,0,1] neg_lo:[1,0,0] neg_hi:[1,0,0]
	v_mul_f32_e32 v29, v29, v18
	v_mul_f32_e32 v24, v25, v18
	v_bfe_u32 v34, v29, 16, 1
	v_bfe_u32 v25, v24, 16, 1
	v_add3_u32 v29, v29, v34, s15
	v_add3_u32 v34, v38, v195, v27
	v_add3_u32 v24, v24, v25, s15
	v_add3_u32 v25, v38, v193, v27
	ds_write_b16_d16_hi v34, v29 offset:13568
	ds_write_b16_d16_hi v25, v24 offset:13824
	v_pk_fma_f32 v[24:25], v[40:41], s[22:23], v[32:33] op_sel_hi:[1,0,1] neg_lo:[1,0,0] neg_hi:[1,0,0]
	v_and_b32_e32 v167, 15, v43
	v_mul_f32_e32 v24, v25, v18
	v_bfe_u32 v25, v24, 16, 1
	v_add3_u32 v24, v24, v25, s15
	v_add3_u32 v25, v38, v191, v27
	ds_write_b16_d16_hi v25, v24 offset:14080
	v_fma_f32 v24, v28, v18, v215
	v_cvt_pk_bf16_f32 v24, v24, v24
	ds_write_b16 v35, v24 offset:14336
	v_sub_f32_e32 v24, v22, v39
	v_pk_fma_f32 v[22:23], v[40:41], s[22:23], v[22:23] op_sel_hi:[1,0,1] neg_lo:[1,0,0] neg_hi:[1,0,0]
	v_mul_f32_e32 v24, v24, v18
	v_mul_f32_e32 v22, v23, v18
	v_bfe_u32 v25, v24, 16, 1
	v_bfe_u32 v23, v22, 16, 1
	v_add3_u32 v24, v24, v25, s15
	v_add3_u32 v22, v22, v23, s15
	ds_write_b16_d16_hi v55, v24 offset:14592
	ds_write_b16_d16_hi v56, v22 offset:14848
	v_pk_fma_f32 v[22:23], v[40:41], s[22:23], v[30:31] op_sel_hi:[1,0,1] neg_lo:[1,0,0] neg_hi:[1,0,0]
	s_nop 0
	v_mul_f32_e32 v22, v23, v18
	v_bfe_u32 v23, v22, 16, 1
	v_add3_u32 v22, v22, v23, s15
	ds_write_b16_d16_hi v54, v22 offset:15104
	v_fma_f32 v22, v26, v18, v215
	v_cvt_pk_bf16_f32 v22, v22, v22
	ds_write_b16 v53, v22 offset:15360
	v_sub_f32_e32 v22, v20, v39
	v_pk_fma_f32 v[20:21], v[40:41], s[22:23], v[20:21] op_sel_hi:[1,0,1] neg_lo:[1,0,0] neg_hi:[1,0,0]
	v_mul_f32_e32 v22, v22, v18
	v_mul_f32_e32 v20, v21, v18
	v_mul_f32_e32 v18, v19, v18
	v_bfe_u32 v23, v22, 16, 1
	v_bfe_u32 v21, v20, 16, 1
	v_bfe_u32 v19, v18, 16, 1
	v_add3_u32 v22, v22, v23, s15
	v_add3_u32 v20, v20, v21, s15
	v_add3_u32 v18, v18, v19, s15
	ds_write_b16_d16_hi v51, v22 offset:15616
	ds_write_b16_d16_hi v49, v20 offset:15872
	ds_write_b16_d16_hi v45, v18 offset:16128
	v_lshrrev_b32_e32 v18, 1, v43
	v_and_b32_e32 v18, 32, v18
	v_lshl_or_b32 v166, v44, 6, v18
	v_or_b32_e32 v18, v166, v168
	v_lshl_add_u32 v165, v18, 8, 32
	v_bitop3_b32 v18, v42, v167, 1 bitop3:0x6c
	v_lshl_add_u32 v18, v18, 4, v165
	s_waitcnt lgkmcnt(0)
	s_barrier
	ds_read_b128 v[170:173], v18 offset:55296
	s_waitcnt lgkmcnt(0)
	v_mfma_f32_32x32x16_bf16 v[50:65], v[170:173], v[2:5], 0
	v_mfma_f32_32x32x16_bf16 v[34:49], v[170:173], v[6:9], 0
	v_mfma_f32_32x32x16_bf16 v[18:33], v[170:173], v[10:13], 0
	v_mfma_f32_32x32x16_bf16 v[2:17], v[170:173], v[14:17], 0
	v_bitop3_b32 v170, v169, v167, 2 bitop3:0x36
	v_lshl_add_u32 v170, v170, 4, v165
	ds_read_b128 v[170:173], v170 offset:55296
	s_waitcnt lgkmcnt(0)
	v_mfma_f32_32x32x16_bf16 v[50:65], v[170:173], v[138:141], v[50:65]
	v_bitop3_b32 v138, v169, v167, 4 bitop3:0x36
	v_lshl_add_u32 v138, v138, 4, v165
	ds_read_b128 v[138:141], v138 offset:55296
	v_mfma_f32_32x32x16_bf16 v[34:49], v[170:173], v[142:145], v[34:49]
	v_mfma_f32_32x32x16_bf16 v[18:33], v[170:173], v[146:149], v[18:33]
	s_waitcnt lgkmcnt(0)
	v_mfma_f32_32x32x16_bf16 v[34:49], v[138:141], v[126:129], v[34:49]
	v_bitop3_b32 v126, v169, v167, 6 bitop3:0x36
	v_lshl_add_u32 v126, v126, 4, v165
	ds_read_b128 v[126:129], v126 offset:55296
	v_mfma_f32_32x32x16_bf16 v[2:17], v[170:173], v[150:153], v[2:17]
	v_mfma_f32_32x32x16_bf16 v[18:33], v[138:141], v[130:133], v[18:33]
	s_waitcnt lgkmcnt(0)
	v_mfma_f32_32x32x16_bf16 v[34:49], v[126:129], v[114:117], v[34:49]
	v_bitop3_b32 v114, v169, v167, 8 bitop3:0x36
	v_lshl_add_u32 v114, v114, 4, v165
	ds_read_b128 v[114:117], v114 offset:55296
	v_mfma_f32_32x32x16_bf16 v[2:17], v[138:141], v[134:137], v[2:17]
	v_mfma_f32_32x32x16_bf16 v[18:33], v[126:129], v[118:121], v[18:33]
	v_mfma_f32_32x32x16_bf16 v[2:17], v[126:129], v[122:125], v[2:17]
	v_lshlrev_b32_e32 v128, 7, v164
	v_or_b32_e32 v126, v128, v168
	v_ashrrev_i32_e32 v127, 31, v126
	v_lshlrev_b64 v[130:131], 2, v[126:127]
	v_lshl_or_b32 v122, v169, 2, v166
	v_or_b32_e32 v124, s3, v168
	v_mov_b32_e32 v125, s5
	s_waitcnt lgkmcnt(0)
	v_mfma_f32_32x32x16_bf16 v[18:33], v[114:117], v[106:109], v[18:33]
	v_bitop3_b32 v106, v169, v167, 10 bitop3:0x36
	v_lshl_add_u32 v106, v106, 4, v165
	ds_read_b128 v[106:109], v106 offset:55296
	v_lshl_add_u64 v[132:133], s[6:7], 0, v[130:131]
	v_lshl_add_u64 v[130:131], s[92:93], 0, v[130:131]
	v_ashrrev_i32_e32 v123, 31, v122
	v_lshlrev_b64 v[122:123], 1, v[122:123]
	v_mfma_f32_32x32x16_bf16 v[2:17], v[114:117], v[110:113], v[2:17]
	s_add_i32 s3, s3, s18
	s_cmpk_gt_i32 s4, 0x7f
	s_waitcnt lgkmcnt(0)
	v_mfma_f32_32x32x16_bf16 v[18:33], v[106:109], v[98:101], v[18:33]
	v_bitop3_b32 v98, v169, v167, 12 bitop3:0x36
	v_lshl_add_u32 v98, v98, 4, v165
	ds_read_b128 v[98:101], v98 offset:55296
	v_mfma_f32_32x32x16_bf16 v[2:17], v[106:109], v[102:105], v[2:17]
	s_waitcnt lgkmcnt(0)
	v_mfma_f32_32x32x16_bf16 v[2:17], v[98:101], v[94:97], v[2:17]
	v_bitop3_b32 v94, v169, v167, 14 bitop3:0x36
	v_lshl_add_u32 v94, v94, 4, v165
	ds_read_b128 v[94:97], v94 offset:55296
	v_ashrrev_i32_e32 v167, 31, v166
	s_waitcnt lgkmcnt(0)
	v_mfma_f32_32x32x16_bf16 v[2:17], v[94:97], v[90:93], v[2:17]
	v_lshlrev_b64 v[90:91], 2, v[166:167]
	v_lshl_add_u64 v[92:93], s[10:11], 0, v[90:91]
	v_lshl_add_u64 v[90:91], s[40:41], 0, v[90:91]
	v_lshl_add_u64 v[92:93], v[92:93], 0, v[154:155]
	v_lshl_add_u64 v[94:95], v[90:91], 0, v[154:155]
	global_load_dwordx4 v[114:117], v[92:93], off
	global_load_dwordx4 v[118:121], v[94:95], off
	global_load_dwordx4 v[106:109], v[92:93], off offset:32
	global_load_dwordx4 v[110:113], v[94:95], off offset:32
	global_load_dwordx4 v[98:101], v[92:93], off offset:64
	global_load_dwordx4 v[102:105], v[94:95], off offset:64
	s_nop 0
	global_load_dwordx4 v[90:93], v[92:93], off offset:96
	s_nop 0
	global_load_dwordx4 v[94:97], v[94:95], off offset:96
	s_nop 0
	global_load_dword v186, v[132:133], off
	global_load_dword v187, v[132:133], off offset:128
	global_load_dword v188, v[132:133], off offset:256
	global_load_dword v189, v[132:133], off offset:384
	global_load_dword v190, v[130:131], off
	global_load_dword v191, v[130:131], off offset:128
	global_load_dword v192, v[130:131], off offset:256
	global_load_dword v193, v[130:131], off offset:384
	v_lshlrev_b64 v[176:177], 11, v[124:125]
	v_lshl_add_u64 v[176:177], s[62:63], 0, v[176:177]
	v_lshl_add_u64 v[176:177], v[176:177], 0, v[122:123]
	v_bfe_u32 v195, v0, 5, 1
	v_lshlrev_b32_e32 v195, 3, v195
	v_add_co_u32_e32 v176, vcc, v176, v195
	s_nop 1
	v_addc_co_u32_e32 v177, vcc, 0, v177, vcc
	v_add_co_u32_e32 v178, vcc, 0x10000, v176
	s_nop 1
	v_addc_co_u32_e32 v179, vcc, 0, v177, vcc
	v_add_co_u32_e32 v182, vcc, 0x20000, v176
	s_nop 1
	v_addc_co_u32_e32 v183, vcc, 0, v177, vcc
	v_add_co_u32_e32 v184, vcc, 0x30000, v176
	s_nop 1
	v_addc_co_u32_e32 v185, vcc, 0, v177, vcc
	s_waitcnt vmcnt(0)
	v_mul_f32_e32 v194, v118, v186
	v_fmac_f32_e32 v194, v50, v114
	v_add_f32_e32 v50, v190, v194
	v_lshlrev_b32_e32 v195, 16, v216
	v_mul_f32_e32 v50, v50, v195
	v_mul_f32_e32 v194, v119, v186
	v_fmac_f32_e32 v194, v51, v115
	v_add_f32_e32 v51, v190, v194
	v_and_b32_e32 v195, 0xffff0000, v216
	v_mul_f32_e32 v51, v51, v195
	v_mul_f32_e32 v194, v120, v186
	v_fmac_f32_e32 v194, v52, v116
	v_add_f32_e32 v52, v190, v194
	v_lshlrev_b32_e32 v195, 16, v217
	v_mul_f32_e32 v52, v52, v195
	v_mul_f32_e32 v194, v121, v186
	v_fmac_f32_e32 v194, v53, v117
	v_add_f32_e32 v53, v190, v194
	v_and_b32_e32 v195, 0xffff0000, v217
	v_mul_f32_e32 v53, v53, v195
	v_cvt_pk_bf16_f32 v50, v50, v51
	v_cvt_pk_bf16_f32 v51, v52, v53
	v_mul_f32_e32 v194, v110, v186
	v_fmac_f32_e32 v194, v54, v106
	v_add_f32_e32 v54, v190, v194
	v_lshlrev_b32_e32 v195, 16, v218
	v_mul_f32_e32 v54, v54, v195
	v_mul_f32_e32 v194, v111, v186
	v_fmac_f32_e32 v194, v55, v107
	v_add_f32_e32 v55, v190, v194
	v_and_b32_e32 v195, 0xffff0000, v218
	v_mul_f32_e32 v55, v55, v195
	v_mul_f32_e32 v194, v112, v186
	v_fmac_f32_e32 v194, v56, v108
	v_add_f32_e32 v56, v190, v194
	v_lshlrev_b32_e32 v195, 16, v219
	v_mul_f32_e32 v56, v56, v195
	v_mul_f32_e32 v194, v113, v186
	v_fmac_f32_e32 v194, v57, v109
	v_add_f32_e32 v57, v190, v194
	v_and_b32_e32 v195, 0xffff0000, v219
	v_mul_f32_e32 v57, v57, v195
	v_cvt_pk_bf16_f32 v52, v54, v55
	v_cvt_pk_bf16_f32 v53, v56, v57
	s_nop 1
	v_permlane32_swap_b32 v50, v52
	v_permlane32_swap_b32 v51, v53
	global_store_dwordx4 v[176:177], v[50:53], off offset:1536
	v_mul_f32_e32 v194, v102, v186
	v_fmac_f32_e32 v194, v58, v98
	v_add_f32_e32 v58, v190, v194
	v_lshlrev_b32_e32 v195, 16, v220
	v_mul_f32_e32 v58, v58, v195
	v_mul_f32_e32 v194, v103, v186
	v_fmac_f32_e32 v194, v59, v99
	v_add_f32_e32 v59, v190, v194
	v_and_b32_e32 v195, 0xffff0000, v220
	v_mul_f32_e32 v59, v59, v195
	v_mul_f32_e32 v194, v104, v186
	v_fmac_f32_e32 v194, v60, v100
	v_add_f32_e32 v60, v190, v194
	v_lshlrev_b32_e32 v195, 16, v221
	v_mul_f32_e32 v60, v60, v195
	v_mul_f32_e32 v194, v105, v186
	v_fmac_f32_e32 v194, v61, v101
	v_add_f32_e32 v61, v190, v194
	v_and_b32_e32 v195, 0xffff0000, v221
	v_mul_f32_e32 v61, v61, v195
	v_cvt_pk_bf16_f32 v58, v58, v59
	v_cvt_pk_bf16_f32 v59, v60, v61
	v_mul_f32_e32 v194, v94, v186
	v_fmac_f32_e32 v194, v62, v90
	v_add_f32_e32 v62, v190, v194
	v_lshlrev_b32_e32 v195, 16, v222
	v_mul_f32_e32 v62, v62, v195
	v_mul_f32_e32 v194, v95, v186
	v_fmac_f32_e32 v194, v63, v91
	v_add_f32_e32 v63, v190, v194
	v_and_b32_e32 v195, 0xffff0000, v222
	v_mul_f32_e32 v63, v63, v195
	v_mul_f32_e32 v194, v96, v186
	v_fmac_f32_e32 v194, v64, v92
	v_add_f32_e32 v64, v190, v194
	v_lshlrev_b32_e32 v195, 16, v223
	v_mul_f32_e32 v64, v64, v195
	v_mul_f32_e32 v194, v97, v186
	v_fmac_f32_e32 v194, v65, v93
	v_add_f32_e32 v65, v190, v194
	v_and_b32_e32 v195, 0xffff0000, v223
	v_mul_f32_e32 v65, v65, v195
	v_cvt_pk_bf16_f32 v60, v62, v63
	v_cvt_pk_bf16_f32 v61, v64, v65
	s_nop 1
	v_permlane32_swap_b32 v58, v60
	v_permlane32_swap_b32 v59, v61
	global_store_dwordx4 v[176:177], v[58:61], off offset:1568
	v_mul_f32_e32 v194, v118, v187
	v_fmac_f32_e32 v194, v34, v114
	v_add_f32_e32 v34, v191, v194
	v_lshlrev_b32_e32 v195, 16, v224
	v_mul_f32_e32 v34, v34, v195
	v_mul_f32_e32 v194, v119, v187
	v_fmac_f32_e32 v194, v35, v115
	v_add_f32_e32 v35, v191, v194
	v_and_b32_e32 v195, 0xffff0000, v224
	v_mul_f32_e32 v35, v35, v195
	v_mul_f32_e32 v194, v120, v187
	v_fmac_f32_e32 v194, v36, v116
	v_add_f32_e32 v36, v191, v194
	v_lshlrev_b32_e32 v195, 16, v225
	v_mul_f32_e32 v36, v36, v195
	v_mul_f32_e32 v194, v121, v187
	v_fmac_f32_e32 v194, v37, v117
	v_add_f32_e32 v37, v191, v194
	v_and_b32_e32 v195, 0xffff0000, v225
	v_mul_f32_e32 v37, v37, v195
	v_cvt_pk_bf16_f32 v34, v34, v35
	v_cvt_pk_bf16_f32 v35, v36, v37
	v_mul_f32_e32 v194, v110, v187
	v_fmac_f32_e32 v194, v38, v106
	v_add_f32_e32 v38, v191, v194
	v_lshlrev_b32_e32 v195, 16, v226
	v_mul_f32_e32 v38, v38, v195
	v_mul_f32_e32 v194, v111, v187
	v_fmac_f32_e32 v194, v39, v107
	v_add_f32_e32 v39, v191, v194
	v_and_b32_e32 v195, 0xffff0000, v226
	v_mul_f32_e32 v39, v39, v195
	v_mul_f32_e32 v194, v112, v187
	v_fmac_f32_e32 v194, v40, v108
	v_add_f32_e32 v40, v191, v194
	v_lshlrev_b32_e32 v195, 16, v227
	v_mul_f32_e32 v40, v40, v195
	v_mul_f32_e32 v194, v113, v187
	v_fmac_f32_e32 v194, v41, v109
	v_add_f32_e32 v41, v191, v194
	v_and_b32_e32 v195, 0xffff0000, v227
	v_mul_f32_e32 v41, v41, v195
	v_cvt_pk_bf16_f32 v36, v38, v39
	v_cvt_pk_bf16_f32 v37, v40, v41
	s_nop 1
	v_permlane32_swap_b32 v34, v36
	v_permlane32_swap_b32 v35, v37
	global_store_dwordx4 v[178:179], v[34:37], off offset:1536
	v_mul_f32_e32 v194, v102, v187
	v_fmac_f32_e32 v194, v42, v98
	v_add_f32_e32 v42, v191, v194
	v_lshlrev_b32_e32 v195, 16, v228
	v_mul_f32_e32 v42, v42, v195
	v_mul_f32_e32 v194, v103, v187
	v_fmac_f32_e32 v194, v43, v99
	v_add_f32_e32 v43, v191, v194
	v_and_b32_e32 v195, 0xffff0000, v228
	v_mul_f32_e32 v43, v43, v195
	v_mul_f32_e32 v194, v104, v187
	v_fmac_f32_e32 v194, v44, v100
	v_add_f32_e32 v44, v191, v194
	v_lshlrev_b32_e32 v195, 16, v229
	v_mul_f32_e32 v44, v44, v195
	v_mul_f32_e32 v194, v105, v187
	v_fmac_f32_e32 v194, v45, v101
	v_add_f32_e32 v45, v191, v194
	v_and_b32_e32 v195, 0xffff0000, v229
	v_mul_f32_e32 v45, v45, v195
	v_cvt_pk_bf16_f32 v42, v42, v43
	v_cvt_pk_bf16_f32 v43, v44, v45
	v_mul_f32_e32 v194, v94, v187
	v_fmac_f32_e32 v194, v46, v90
	v_add_f32_e32 v46, v191, v194
	v_lshlrev_b32_e32 v195, 16, v230
	v_mul_f32_e32 v46, v46, v195
	v_mul_f32_e32 v194, v95, v187
	v_fmac_f32_e32 v194, v47, v91
	v_add_f32_e32 v47, v191, v194
	v_and_b32_e32 v195, 0xffff0000, v230
	v_mul_f32_e32 v47, v47, v195
	v_mul_f32_e32 v194, v96, v187
	v_fmac_f32_e32 v194, v48, v92
	v_add_f32_e32 v48, v191, v194
	v_lshlrev_b32_e32 v195, 16, v231
	v_mul_f32_e32 v48, v48, v195
	v_mul_f32_e32 v194, v97, v187
	v_fmac_f32_e32 v194, v49, v93
	v_add_f32_e32 v49, v191, v194
	v_and_b32_e32 v195, 0xffff0000, v231
	v_mul_f32_e32 v49, v49, v195
	v_cvt_pk_bf16_f32 v44, v46, v47
	v_cvt_pk_bf16_f32 v45, v48, v49
	s_nop 1
	v_permlane32_swap_b32 v42, v44
	v_permlane32_swap_b32 v43, v45
	global_store_dwordx4 v[178:179], v[42:45], off offset:1568
	v_mul_f32_e32 v194, v118, v188
	v_fmac_f32_e32 v194, v18, v114
	v_add_f32_e32 v18, v192, v194
	v_lshlrev_b32_e32 v195, 16, v232
	v_mul_f32_e32 v18, v18, v195
	v_mul_f32_e32 v194, v119, v188
	v_fmac_f32_e32 v194, v19, v115
	v_add_f32_e32 v19, v192, v194
	v_and_b32_e32 v195, 0xffff0000, v232
	v_mul_f32_e32 v19, v19, v195
	v_mul_f32_e32 v194, v120, v188
	v_fmac_f32_e32 v194, v20, v116
	v_add_f32_e32 v20, v192, v194
	v_lshlrev_b32_e32 v195, 16, v233
	v_mul_f32_e32 v20, v20, v195
	v_mul_f32_e32 v194, v121, v188
	v_fmac_f32_e32 v194, v21, v117
	v_add_f32_e32 v21, v192, v194
	v_and_b32_e32 v195, 0xffff0000, v233
	v_mul_f32_e32 v21, v21, v195
	v_cvt_pk_bf16_f32 v18, v18, v19
	v_cvt_pk_bf16_f32 v19, v20, v21
	v_mul_f32_e32 v194, v110, v188
	v_fmac_f32_e32 v194, v22, v106
	v_add_f32_e32 v22, v192, v194
	v_lshlrev_b32_e32 v195, 16, v234
	v_mul_f32_e32 v22, v22, v195
	v_mul_f32_e32 v194, v111, v188
	v_fmac_f32_e32 v194, v23, v107
	v_add_f32_e32 v23, v192, v194
	v_and_b32_e32 v195, 0xffff0000, v234
	v_mul_f32_e32 v23, v23, v195
	v_mul_f32_e32 v194, v112, v188
	v_fmac_f32_e32 v194, v24, v108
	v_add_f32_e32 v24, v192, v194
	v_lshlrev_b32_e32 v195, 16, v235
	v_mul_f32_e32 v24, v24, v195
	v_mul_f32_e32 v194, v113, v188
	v_fmac_f32_e32 v194, v25, v109
	v_add_f32_e32 v25, v192, v194
	v_and_b32_e32 v195, 0xffff0000, v235
	v_mul_f32_e32 v25, v25, v195
	v_cvt_pk_bf16_f32 v20, v22, v23
	v_cvt_pk_bf16_f32 v21, v24, v25
	s_nop 1
	v_permlane32_swap_b32 v18, v20
	v_permlane32_swap_b32 v19, v21
	global_store_dwordx4 v[182:183], v[18:21], off offset:1536
	v_mul_f32_e32 v194, v102, v188
	v_fmac_f32_e32 v194, v26, v98
	v_add_f32_e32 v26, v192, v194
	v_lshlrev_b32_e32 v195, 16, v236
	v_mul_f32_e32 v26, v26, v195
	v_mul_f32_e32 v194, v103, v188
	v_fmac_f32_e32 v194, v27, v99
	v_add_f32_e32 v27, v192, v194
	v_and_b32_e32 v195, 0xffff0000, v236
	v_mul_f32_e32 v27, v27, v195
	v_mul_f32_e32 v194, v104, v188
	v_fmac_f32_e32 v194, v28, v100
	v_add_f32_e32 v28, v192, v194
	v_lshlrev_b32_e32 v195, 16, v237
	v_mul_f32_e32 v28, v28, v195
	v_mul_f32_e32 v194, v105, v188
	v_fmac_f32_e32 v194, v29, v101
	v_add_f32_e32 v29, v192, v194
	v_and_b32_e32 v195, 0xffff0000, v237
	v_mul_f32_e32 v29, v29, v195
	v_cvt_pk_bf16_f32 v26, v26, v27
	v_cvt_pk_bf16_f32 v27, v28, v29
	v_mul_f32_e32 v194, v94, v188
	v_fmac_f32_e32 v194, v30, v90
	v_add_f32_e32 v30, v192, v194
	v_lshlrev_b32_e32 v195, 16, v238
	v_mul_f32_e32 v30, v30, v195
	v_mul_f32_e32 v194, v95, v188
	v_fmac_f32_e32 v194, v31, v91
	v_add_f32_e32 v31, v192, v194
	v_and_b32_e32 v195, 0xffff0000, v238
	v_mul_f32_e32 v31, v31, v195
	v_mul_f32_e32 v194, v96, v188
	v_fmac_f32_e32 v194, v32, v92
	v_add_f32_e32 v32, v192, v194
	v_lshlrev_b32_e32 v195, 16, v239
	v_mul_f32_e32 v32, v32, v195
	v_mul_f32_e32 v194, v97, v188
	v_fmac_f32_e32 v194, v33, v93
	v_add_f32_e32 v33, v192, v194
	v_and_b32_e32 v195, 0xffff0000, v239
	v_mul_f32_e32 v33, v33, v195
	v_cvt_pk_bf16_f32 v28, v30, v31
	v_cvt_pk_bf16_f32 v29, v32, v33
	s_nop 1
	v_permlane32_swap_b32 v26, v28
	v_permlane32_swap_b32 v27, v29
	global_store_dwordx4 v[182:183], v[26:29], off offset:1568
	v_mul_f32_e32 v194, v118, v189
	v_fmac_f32_e32 v194, v2, v114
	v_add_f32_e32 v2, v193, v194
	v_lshlrev_b32_e32 v195, 16, v240
	v_mul_f32_e32 v2, v2, v195
	v_mul_f32_e32 v194, v119, v189
	v_fmac_f32_e32 v194, v3, v115
	v_add_f32_e32 v3, v193, v194
	v_and_b32_e32 v195, 0xffff0000, v240
	v_mul_f32_e32 v3, v3, v195
	v_mul_f32_e32 v194, v120, v189
	v_fmac_f32_e32 v194, v4, v116
	v_add_f32_e32 v4, v193, v194
	v_lshlrev_b32_e32 v195, 16, v241
	v_mul_f32_e32 v4, v4, v195
	v_mul_f32_e32 v194, v121, v189
	v_fmac_f32_e32 v194, v5, v117
	v_add_f32_e32 v5, v193, v194
	v_and_b32_e32 v195, 0xffff0000, v241
	v_mul_f32_e32 v5, v5, v195
	v_cvt_pk_bf16_f32 v2, v2, v3
	v_cvt_pk_bf16_f32 v3, v4, v5
	v_mul_f32_e32 v194, v110, v189
	v_fmac_f32_e32 v194, v6, v106
	v_add_f32_e32 v6, v193, v194
	v_lshlrev_b32_e32 v195, 16, v246
	v_mul_f32_e32 v6, v6, v195
	v_mul_f32_e32 v194, v111, v189
	v_fmac_f32_e32 v194, v7, v107
	v_add_f32_e32 v7, v193, v194
	v_and_b32_e32 v195, 0xffff0000, v246
	v_mul_f32_e32 v7, v7, v195
	v_mul_f32_e32 v194, v112, v189
	v_fmac_f32_e32 v194, v8, v108
	v_add_f32_e32 v8, v193, v194
	v_lshlrev_b32_e32 v195, 16, v247
	v_mul_f32_e32 v8, v8, v195
	v_mul_f32_e32 v194, v113, v189
	v_fmac_f32_e32 v194, v9, v109
	v_add_f32_e32 v9, v193, v194
	v_and_b32_e32 v195, 0xffff0000, v247
	v_mul_f32_e32 v9, v9, v195
	v_cvt_pk_bf16_f32 v4, v6, v7
	v_cvt_pk_bf16_f32 v5, v8, v9
	s_nop 1
	v_permlane32_swap_b32 v2, v4
	v_permlane32_swap_b32 v3, v5
	global_store_dwordx4 v[184:185], v[2:5], off offset:1536
	v_mul_f32_e32 v194, v102, v189
	v_fmac_f32_e32 v194, v10, v98
	v_add_f32_e32 v10, v193, v194
	v_lshlrev_b32_e32 v195, 16, v252
	v_mul_f32_e32 v10, v10, v195
	v_mul_f32_e32 v194, v103, v189
	v_fmac_f32_e32 v194, v11, v99
	v_add_f32_e32 v11, v193, v194
	v_and_b32_e32 v195, 0xffff0000, v252
	v_mul_f32_e32 v11, v11, v195
	v_mul_f32_e32 v194, v104, v189
	v_fmac_f32_e32 v194, v12, v100
	v_add_f32_e32 v12, v193, v194
	v_lshlrev_b32_e32 v195, 16, v253
	v_mul_f32_e32 v12, v12, v195
	v_mul_f32_e32 v194, v105, v189
	v_fmac_f32_e32 v194, v13, v101
	v_add_f32_e32 v13, v193, v194
	v_and_b32_e32 v195, 0xffff0000, v253
	v_mul_f32_e32 v13, v13, v195
	v_cvt_pk_bf16_f32 v10, v10, v11
	v_cvt_pk_bf16_f32 v11, v12, v13
	v_mul_f32_e32 v194, v94, v189
	v_fmac_f32_e32 v194, v14, v90
	v_add_f32_e32 v14, v193, v194
	v_lshlrev_b32_e32 v195, 16, v254
	v_mul_f32_e32 v14, v14, v195
	v_mul_f32_e32 v194, v95, v189
	v_fmac_f32_e32 v194, v15, v91
	v_add_f32_e32 v15, v193, v194
	v_and_b32_e32 v195, 0xffff0000, v254
	v_mul_f32_e32 v15, v15, v195
	v_mul_f32_e32 v194, v96, v189
	v_fmac_f32_e32 v194, v16, v92
	v_add_f32_e32 v16, v193, v194
	v_lshlrev_b32_e32 v195, 16, v255
	v_mul_f32_e32 v16, v16, v195
	v_mul_f32_e32 v194, v97, v189
	v_fmac_f32_e32 v194, v17, v93
	v_add_f32_e32 v17, v193, v194
	v_and_b32_e32 v195, 0xffff0000, v255
	v_mul_f32_e32 v17, v17, v195
	v_cvt_pk_bf16_f32 v12, v14, v15
	v_cvt_pk_bf16_f32 v13, v16, v17
	s_nop 1
	v_permlane32_swap_b32 v10, v12
	v_permlane32_swap_b32 v11, v13
	global_store_dwordx4 v[184:185], v[10:13], off offset:1568
	s_barrier
	s_cbranch_scc0 .LBB0_779

.LBB0_849:
	v_mov_b32_e32 v43, v0
	s_ashr_i32 s5, s3, 31
	v_ashrrev_i32_e32 v44, 7, v43
	s_waitcnt vmcnt(7)
	v_add_u32_e32 v130, s2, v44
	v_ashrrev_i32_e32 v131, 31, v130
	v_and_b32_e32 v134, 31, v43
	s_waitcnt vmcnt(0)
	v_lshlrev_b64 v[2:3], 15, v[130:131]
	v_bfe_u32 v135, v43, 5, 1
	v_lshl_add_u64 v[2:3], s[56:57], 0, v[2:3]
	v_lshlrev_b32_e32 v154, 8, v134
	v_lshl_add_u64 v[2:3], v[2:3], 0, v[154:155]
	v_lshlrev_b32_e32 v154, 4, v135
	v_lshl_add_u64 v[18:19], v[2:3], 0, v[154:155]
	v_add_co_u32_e32 v20, vcc, s14, v18
	v_ashrrev_i32_e32 v45, 2, v43
	s_nop 0
	v_addc_co_u32_e32 v21, vcc, 0, v19, vcc
	v_add_co_u32_e32 v22, vcc, s17, v18
	global_load_dwordx4 v[2:5], v[18:19], off
	global_load_dwordx4 v[6:9], v[20:21], off
	v_addc_co_u32_e32 v23, vcc, 0, v19, vcc
	v_add_co_u32_e32 v24, vcc, s30, v18
	global_load_dwordx4 v[10:13], v[22:23], off
	s_nop 0
	v_addc_co_u32_e32 v25, vcc, 0, v19, vcc
	global_load_dwordx4 v[14:17], v[24:25], off
	global_load_dwordx4 v[114:117], v[18:19], off offset:32
	global_load_dwordx4 v[118:121], v[20:21], off offset:32
	global_load_dwordx4 v[122:125], v[22:23], off offset:32
	global_load_dwordx4 v[126:129], v[24:25], off offset:32
	global_load_dwordx4 v[102:105], v[20:21], off offset:64
	global_load_dwordx4 v[106:109], v[22:23], off offset:64
	global_load_dwordx4 v[110:113], v[24:25], off offset:64
	global_load_dwordx4 v[90:93], v[20:21], off offset:96
	global_load_dwordx4 v[94:97], v[22:23], off offset:96
	global_load_dwordx4 v[98:101], v[24:25], off offset:96
	global_load_dwordx4 v[82:85], v[22:23], off offset:128
	global_load_dwordx4 v[86:89], v[24:25], off offset:128
	global_load_dwordx4 v[74:77], v[22:23], off offset:160
	global_load_dwordx4 v[78:81], v[24:25], off offset:160
	global_load_dwordx4 v[70:73], v[24:25], off offset:192
	global_load_dwordx4 v[66:69], v[24:25], off offset:224
	v_add_u32_e32 v18, s3, v45
	v_ashrrev_i32_e32 v19, 31, v18
	v_lshlrev_b32_e32 v20, 6, v43
	v_lshlrev_b64 v[18:19], 12, v[18:19]
	v_and_b32_e32 v46, 0xc0, v20
	v_lshl_add_u64 v[18:19], s[60:61], 0, v[18:19]
	v_lshlrev_b32_e32 v20, 1, v46
	v_mov_b32_e32 v21, v155
	v_lshl_add_u64 v[34:35], v[18:19], 0, v[20:21]
	global_load_dwordx4 v[18:21], v[34:35], off offset:3632
	global_load_dwordx4 v[22:25], v[34:35], off offset:3616
	global_load_dwordx4 v[26:29], v[34:35], off offset:3600
	global_load_dwordx4 v[30:33], v[34:35], off offset:3584
	global_load_dwordx4 v[36:39], v[34:35], off offset:3680
	global_load_dwordx4 v[176:179], v[34:35], off offset:3664
	global_load_dwordx4 v[48:51], v[34:35], off offset:3648
	global_load_dwordx4 v[182:185], v[34:35], off offset:3696
	v_and_b32_e32 v215, 31, v0
	v_add_u32_e32 v215, s3, v215
	v_lshlrev_b32_e32 v215, 12, v215
	v_and_b32_e32 v245, 0x1c0, v0
	v_add_u32_e32 v215, v215, v245
	v_bfe_u32 v245, v0, 5, 1
	v_lshl_add_u32 v215, v245, 3, v215
	global_load_dwordx2 v[216:217], v215, s[60:61] offset:3072
	global_load_dwordx2 v[218:219], v215, s[60:61] offset:3088
	global_load_dwordx2 v[220:221], v215, s[60:61] offset:3104
	global_load_dwordx2 v[222:223], v215, s[60:61] offset:3120
	s_add_u32 s98, s60, 0x20000
	s_addc_u32 s99, s61, 0
	global_load_dwordx2 v[224:225], v215, s[98:99] offset:3072
	global_load_dwordx2 v[226:227], v215, s[98:99] offset:3088
	global_load_dwordx2 v[228:229], v215, s[98:99] offset:3104
	global_load_dwordx2 v[230:231], v215, s[98:99] offset:3120
	s_add_u32 s100, s60, 0x40000
	s_addc_u32 s101, s61, 0
	global_load_dwordx2 v[232:233], v215, s[100:101] offset:3072
	global_load_dwordx2 v[234:235], v215, s[100:101] offset:3088
	global_load_dwordx2 v[236:237], v215, s[100:101] offset:3104
	global_load_dwordx2 v[238:239], v215, s[100:101] offset:3120
	s_add_u32 s98, s60, 0x60000
	s_addc_u32 s99, s61, 0
	global_load_dwordx2 v[240:241], v215, s[98:99] offset:3072
	global_load_dwordx2 v[246:247], v215, s[98:99] offset:3088
	global_load_dwordx2 v[252:253], v215, s[98:99] offset:3104
	global_load_dwordx2 v[254:255], v215, s[98:99] offset:3120
	v_lshrrev_b32_e32 v42, 5, v43
	s_add_i32 s4, s4, s46
	s_waitcnt vmcnt(23)
	v_lshlrev_b32_e32 v144, 16, v18
	s_waitcnt vmcnt(22)
	v_lshlrev_b32_e32 v150, 16, v22
	s_waitcnt vmcnt(21)
	v_lshlrev_b32_e32 v168, 16, v26
	s_waitcnt vmcnt(20)
	v_lshlrev_b32_e32 v174, 16, v30
	v_and_b32_e32 v173, 0xffff0000, v30
	v_add_f32_e32 v30, 0, v174
	v_lshlrev_b32_e32 v172, 16, v31
	v_add_f32_e32 v30, v30, v173
	v_and_b32_e32 v171, 0xffff0000, v31
	v_mul_f32_e32 v31, v173, v173
	v_add_f32_e32 v30, v30, v172
	v_lshlrev_b32_e32 v170, 16, v32
	v_fmac_f32_e32 v31, v174, v174
	v_add_f32_e32 v30, v30, v171
	v_and_b32_e32 v169, 0xffff0000, v32
	v_fmac_f32_e32 v31, v172, v172
	v_add_f32_e32 v30, v30, v170
	v_lshlrev_b32_e32 v167, 16, v33
	v_fmac_f32_e32 v31, v171, v171
	v_add_f32_e32 v30, v30, v169
	v_and_b32_e32 v165, 0xffff0000, v33
	v_fmac_f32_e32 v31, v170, v170
	v_add_f32_e32 v30, v30, v167
	v_fmac_f32_e32 v31, v169, v169
	v_add_f32_e32 v30, v30, v165
	v_fmac_f32_e32 v31, v167, v167
	v_and_b32_e32 v166, 0xffff0000, v26
	v_add_f32_e32 v26, v30, v168
	v_fmac_f32_e32 v31, v165, v165
	v_lshlrev_b32_e32 v164, 16, v27
	v_add_f32_e32 v26, v26, v166
	v_and_b32_e32 v153, 0xffff0000, v27
	v_fmac_f32_e32 v31, v168, v168
	v_add_f32_e32 v26, v26, v164
	v_lshlrev_b32_e32 v152, 16, v28
	v_fmac_f32_e32 v31, v166, v166
	v_add_f32_e32 v26, v26, v153
	v_and_b32_e32 v151, 0xffff0000, v28
	v_fmac_f32_e32 v31, v164, v164
	v_add_f32_e32 v26, v26, v152
	v_lshlrev_b32_e32 v148, 16, v29
	v_fmac_f32_e32 v31, v153, v153
	v_add_f32_e32 v26, v26, v151
	v_and_b32_e32 v146, 0xffff0000, v29
	v_fmac_f32_e32 v31, v152, v152
	v_add_f32_e32 v26, v26, v148
	v_fmac_f32_e32 v31, v151, v151
	v_add_f32_e32 v26, v26, v146
	v_fmac_f32_e32 v31, v148, v148
	v_and_b32_e32 v149, 0xffff0000, v22
	v_add_f32_e32 v22, v26, v150
	v_fmac_f32_e32 v31, v146, v146
	v_lshlrev_b32_e32 v147, 16, v23
	v_add_f32_e32 v22, v22, v149
	v_and_b32_e32 v145, 0xffff0000, v23
	v_fmac_f32_e32 v31, v150, v150
	v_add_f32_e32 v22, v22, v147
	v_lshlrev_b32_e32 v143, 16, v24
	v_fmac_f32_e32 v31, v149, v149
	v_add_f32_e32 v22, v22, v145
	v_and_b32_e32 v141, 0xffff0000, v24
	v_fmac_f32_e32 v31, v147, v147
	v_add_f32_e32 v22, v22, v143
	v_lshlrev_b32_e32 v139, 16, v25
	v_fmac_f32_e32 v31, v145, v145
	v_add_f32_e32 v22, v22, v141
	v_and_b32_e32 v137, 0xffff0000, v25
	v_fmac_f32_e32 v31, v143, v143
	v_add_f32_e32 v22, v22, v139
	v_fmac_f32_e32 v31, v141, v141
	v_add_f32_e32 v22, v22, v137
	v_fmac_f32_e32 v31, v139, v139
	v_and_b32_e32 v142, 0xffff0000, v18
	v_add_f32_e32 v18, v22, v144
	v_fmac_f32_e32 v31, v137, v137
	v_lshlrev_b32_e32 v140, 16, v19
	v_add_f32_e32 v18, v18, v142
	v_and_b32_e32 v138, 0xffff0000, v19
	v_fmac_f32_e32 v31, v144, v144
	v_add_f32_e32 v18, v18, v140
	v_lshlrev_b32_e32 v133, 16, v20
	v_fmac_f32_e32 v31, v142, v142
	v_add_f32_e32 v18, v18, v138
	v_and_b32_e32 v131, 0xffff0000, v20
	v_fmac_f32_e32 v31, v140, v140
	v_add_f32_e32 v18, v18, v133
	v_lshlrev_b32_e32 v64, 16, v21
	v_fmac_f32_e32 v31, v138, v138
	v_add_f32_e32 v18, v18, v131
	v_and_b32_e32 v62, 0xffff0000, v21
	v_fmac_f32_e32 v31, v133, v133
	v_add_f32_e32 v18, v18, v64
	v_fmac_f32_e32 v31, v131, v131
	v_add_f32_e32 v18, v18, v62
	s_waitcnt vmcnt(17)
	v_lshlrev_b32_e32 v136, 16, v48
	v_fmac_f32_e32 v31, v64, v64
	v_and_b32_e32 v132, 0xffff0000, v48
	v_add_f32_e32 v18, v18, v136
	v_fmac_f32_e32 v31, v62, v62
	v_lshlrev_b32_e32 v65, 16, v49
	v_add_f32_e32 v18, v18, v132
	v_and_b32_e32 v63, 0xffff0000, v49
	v_fmac_f32_e32 v31, v136, v136
	v_add_f32_e32 v18, v18, v65
	v_lshlrev_b32_e32 v60, 16, v50
	v_fmac_f32_e32 v31, v132, v132
	v_add_f32_e32 v18, v18, v63
	v_and_b32_e32 v59, 0xffff0000, v50
	v_fmac_f32_e32 v31, v65, v65
	v_add_f32_e32 v18, v18, v60
	v_lshlrev_b32_e32 v57, 16, v51
	v_fmac_f32_e32 v31, v63, v63
	v_add_f32_e32 v18, v18, v59
	v_and_b32_e32 v55, 0xffff0000, v51
	v_fmac_f32_e32 v31, v60, v60
	v_add_f32_e32 v18, v18, v57
	v_fmac_f32_e32 v31, v59, v59
	v_add_f32_e32 v18, v18, v55
	v_lshlrev_b32_e32 v61, 16, v176
	v_fmac_f32_e32 v31, v57, v57
	v_and_b32_e32 v58, 0xffff0000, v176
	v_add_f32_e32 v18, v18, v61
	v_fmac_f32_e32 v31, v55, v55
	v_lshlrev_b32_e32 v56, 16, v177
	v_add_f32_e32 v18, v18, v58
	v_and_b32_e32 v54, 0xffff0000, v177
	v_fmac_f32_e32 v31, v61, v61
	v_add_f32_e32 v18, v18, v56
	v_lshlrev_b32_e32 v53, 16, v178
	v_fmac_f32_e32 v31, v58, v58
	v_add_f32_e32 v18, v18, v54
	v_and_b32_e32 v51, 0xffff0000, v178
	v_fmac_f32_e32 v31, v56, v56
	v_add_f32_e32 v18, v18, v53
	v_lshlrev_b32_e32 v49, 16, v179
	v_fmac_f32_e32 v31, v54, v54
	v_add_f32_e32 v18, v18, v51
	v_and_b32_e32 v47, 0xffff0000, v179
	v_fmac_f32_e32 v31, v53, v53
	v_add_f32_e32 v18, v18, v49
	v_fmac_f32_e32 v31, v51, v51
	v_add_f32_e32 v18, v18, v47
	v_lshlrev_b32_e32 v52, 16, v36
	v_fmac_f32_e32 v31, v49, v49
	v_and_b32_e32 v50, 0xffff0000, v36
	v_add_f32_e32 v18, v18, v52
	v_fmac_f32_e32 v31, v47, v47
	v_lshlrev_b32_e32 v48, 16, v37
	v_add_f32_e32 v18, v18, v50
	v_fmac_f32_e32 v31, v52, v52
	v_add_f32_e32 v18, v18, v48
	v_and_b32_e32 v37, 0xffff0000, v37
	v_fmac_f32_e32 v31, v50, v50
	v_lshlrev_b32_e32 v34, 16, v38
	v_mov_b32_e32 v35, v37
	v_add_f32_e32 v20, v18, v37
	v_fmac_f32_e32 v31, v48, v48
	v_and_b32_e32 v24, 0xffff0000, v38
	v_pk_mul_f32 v[18:19], v[34:35], v[34:35]
	v_add_f32_e32 v20, v20, v34
	v_lshlrev_b32_e32 v25, 16, v39
	v_add_f32_e32 v19, v19, v31
	v_add_f32_e32 v20, v20, v24
	v_add_f32_e32 v21, v18, v19
	v_pk_mul_f32 v[18:19], v[24:25], v[24:25]
	v_add_f32_e32 v20, v20, v25
	v_and_b32_e32 v33, 0xffff0000, v39
	v_add_f32_e32 v18, v18, v21
	s_waitcnt vmcnt(16)
	v_lshlrev_b32_e32 v28, 16, v182
	v_mov_b32_e32 v29, v33
	v_add_f32_e32 v20, v20, v33
	v_add_f32_e32 v21, v19, v18
	v_and_b32_e32 v22, 0xffff0000, v182
	v_pk_mul_f32 v[18:19], v[28:29], v[28:29]
	v_add_f32_e32 v20, v20, v28
	v_lshlrev_b32_e32 v23, 16, v183
	v_add_f32_e32 v19, v19, v21
	v_add_f32_e32 v20, v20, v22
	v_add_f32_e32 v21, v18, v19
	v_pk_mul_f32 v[18:19], v[22:23], v[22:23]
	v_add_f32_e32 v29, v20, v23
	v_and_b32_e32 v31, 0xffff0000, v183
	v_add_f32_e32 v18, v18, v21
	v_lshlrev_b32_e32 v26, 16, v184
	v_mov_b32_e32 v27, v31
	v_add_f32_e32 v29, v29, v31
	v_and_b32_e32 v36, s0, v38
	v_add_f32_e32 v18, v19, v18
	v_and_b32_e32 v20, 0xffff0000, v184
	v_pk_mul_f32 v[38:39], v[26:27], v[26:27]
	v_add_f32_e32 v27, v29, v26
	v_lshlrev_b32_e32 v21, 16, v185
	v_add_f32_e32 v18, v39, v18
	v_add_f32_e32 v27, v27, v20
	v_and_b32_e32 v29, 64, v181
	v_add_f32_e32 v18, v38, v18
	v_pk_mul_f32 v[40:41], v[20:21], v[20:21]
	v_add_f32_e32 v39, v27, v21
	v_xor_b32_e32 v27, 1, v181
	v_add_u32_e32 v29, 64, v29
	v_and_b32_e32 v19, 0xffff0000, v185
	v_add_f32_e32 v18, v40, v18
	v_cmp_lt_i32_e32 vcc, v27, v29
	v_add_f32_e32 v18, v41, v18
	v_mul_f32_e32 v38, v19, v19
	v_cndmask_b32_e32 v27, v181, v27, vcc
	v_lshlrev_b32_e32 v27, 2, v27
	v_pk_add_f32 v[38:39], v[38:39], v[18:19]
	ds_bpermute_b32 v41, v27, v39
	ds_bpermute_b32 v40, v27, v38
	v_xor_b32_e32 v35, 2, v181
	v_cmp_lt_i32_e32 vcc, v35, v29
	v_and_b32_e32 v30, s0, v182
	v_mov_b32_e32 v32, v36
	v_cndmask_b32_e32 v29, v181, v35, vcc
	v_lshlrev_b32_e32 v29, 2, v29
	s_waitcnt lgkmcnt(0)
	v_pk_add_f32 v[38:39], v[38:39], v[40:41]
	ds_bpermute_b32 v41, v29, v39
	ds_bpermute_b32 v40, v29, v38
	s_waitcnt lgkmcnt(0)
	v_pk_add_f32 v[40:41], v[38:39], v[40:41]
	s_nop 0
	v_pk_mul_f32 v[38:39], v[40:41], s[22:23] op_sel_hi:[1,0]
	v_pk_fma_f32 v[36:37], v[40:41], s[22:23], v[36:37] op_sel_hi:[1,0,1] neg_lo:[1,0,0] neg_hi:[1,0,0]
	v_fma_f32 v18, -v39, v39, v38
	v_max_f32_e32 v18, 0, v18
	v_add_f32_e32 v18, 0x358637bd, v18
	v_cmp_gt_f32_e32 vcc, s33, v18
	v_mul_f32_e32 v27, 0x4b800000, v18
	v_sub_f32_e32 v29, v174, v39
	v_cndmask_b32_e32 v18, v18, v27, vcc
	v_rsq_f32_e32 v18, v18
	v_sub_f32_e32 v19, v19, v39
	v_mul_f32_e32 v27, 0x45800000, v18
	v_cndmask_b32_e32 v18, v18, v27, vcc
	v_mul_f32_e32 v29, v29, v18
	v_lshlrev_b32_e32 v27, 1, v45
	v_bfe_u32 v35, v29, 16, 1
	v_ashrrev_i32_e32 v45, 1, v43
	v_and_b32_e32 v27, 14, v27
	v_add3_u32 v29, v29, v35, s15
	v_lshl_add_u32 v35, v46, 8, 32
	v_and_b32_e32 v46, -16, v45
	v_add3_u32 v174, v35, v46, v27
	ds_write_b16_d16_hi v174, v29 offset:55296
	v_mul_f32_e64 v215, -v39, v18
	v_fma_f32 v29, v173, v18, v215
	v_cvt_pk_bf16_f32 v29, v29, v29
	v_bitop3_b32 v173, v45, 16, -16 bitop3:0x6c
	v_add3_u32 v175, v35, v173, v27
	ds_write_b16 v175, v29 offset:55552
	v_fma_f32 v29, v172, v18, v215
	v_cvt_pk_bf16_f32 v29, v29, v29
	v_bitop3_b32 v172, v45, 32, -16 bitop3:0x6c
	v_add3_u32 v176, v35, v172, v27
	ds_write_b16 v176, v29 offset:55808
	v_fma_f32 v29, v171, v18, v215
	v_cvt_pk_bf16_f32 v29, v29, v29
	v_bitop3_b32 v171, v45, 48, -16 bitop3:0x6c
	v_add3_u32 v177, v35, v171, v27
	ds_write_b16 v177, v29 offset:56064
	v_fma_f32 v29, v170, v18, v215
	v_cvt_pk_bf16_f32 v29, v29, v29
	v_bitop3_b32 v170, v45, 64, -16 bitop3:0x6c
	v_add3_u32 v178, v35, v170, v27
	ds_write_b16 v178, v29 offset:56320
	v_fma_f32 v29, v169, v18, v215
	v_cvt_pk_bf16_f32 v29, v29, v29
	v_bitop3_b32 v169, v45, s34, -16 bitop3:0x6c
	v_add3_u32 v179, v35, v169, v27
	ds_write_b16 v179, v29 offset:56576
	v_fma_f32 v29, v167, v18, v215
	v_cvt_pk_bf16_f32 v29, v29, v29
	v_bitop3_b32 v167, v45, s31, -16 bitop3:0x6c
	v_add3_u32 v182, v35, v167, v27
	ds_write_b16 v182, v29 offset:56832
	v_fma_f32 v29, v165, v18, v215
	v_cvt_pk_bf16_f32 v29, v29, v29
	v_bitop3_b32 v165, v45, s13, -16 bitop3:0x6c
	v_add3_u32 v183, v35, v165, v27
	ds_write_b16 v183, v29 offset:57088
	v_fma_f32 v29, v168, v18, v215
	v_cvt_pk_bf16_f32 v29, v29, v29
	v_bitop3_b32 v168, v45, s12, -16 bitop3:0x6c
	v_add3_u32 v184, v35, v168, v27
	ds_write_b16 v184, v29 offset:57344
	v_fma_f32 v29, v166, v18, v215
	v_cvt_pk_bf16_f32 v29, v29, v29
	v_bitop3_b32 v166, v45, s35, -16 bitop3:0x6c
	v_add3_u32 v185, v35, v166, v27
	ds_write_b16 v185, v29 offset:57600
	v_fma_f32 v29, v164, v18, v215
	v_cvt_pk_bf16_f32 v29, v29, v29
	v_bitop3_b32 v164, v45, s38, -16 bitop3:0x6c
	v_add3_u32 v186, v35, v164, v27
	ds_write_b16 v186, v29 offset:57856
	v_fma_f32 v29, v153, v18, v215
	v_cvt_pk_bf16_f32 v29, v29, v29
	v_bitop3_b32 v153, v45, s39, -16 bitop3:0x6c
	v_add3_u32 v187, v35, v153, v27
	ds_write_b16 v187, v29 offset:58112
	v_fma_f32 v29, v152, v18, v215
	v_cvt_pk_bf16_f32 v29, v29, v29
	v_bitop3_b32 v152, v45, s16, -16 bitop3:0x6c
	v_add3_u32 v188, v35, v152, v27
	ds_write_b16 v188, v29 offset:58368
	v_fma_f32 v29, v151, v18, v215
	v_cvt_pk_bf16_f32 v29, v29, v29
	v_bitop3_b32 v151, v45, s40, -16 bitop3:0x6c
	v_add3_u32 v189, v35, v151, v27
	ds_write_b16 v189, v29 offset:58624
	v_fma_f32 v29, v148, v18, v215
	v_cvt_pk_bf16_f32 v29, v29, v29
	v_bitop3_b32 v148, v45, s41, -16 bitop3:0x6c
	v_add3_u32 v190, v35, v148, v27
	ds_write_b16 v190, v29 offset:58880
	v_sub_f32_e32 v29, v146, v39
	v_mul_f32_e32 v29, v29, v18
	v_bfe_u32 v146, v29, 16, 1
	v_bitop3_b32 v45, v45, s42, -16 bitop3:0x6c
	v_add_u32_e32 v38, 0xd800, v35
	v_add3_u32 v29, v29, v146, s15
	v_add3_u32 v35, v35, v45, v27
	ds_write_b16_d16_hi v35, v29 offset:59136
	v_fma_f32 v29, v150, v18, v215
	v_cvt_pk_bf16_f32 v29, v29, v29
	ds_write_b16 v174, v29 offset:59392
	v_fma_f32 v29, v149, v18, v215
	v_cvt_pk_bf16_f32 v29, v29, v29
	ds_write_b16 v175, v29 offset:59648
	v_fma_f32 v29, v147, v18, v215
	v_cvt_pk_bf16_f32 v29, v29, v29
	ds_write_b16 v176, v29 offset:59904
	v_fma_f32 v29, v145, v18, v215
	v_cvt_pk_bf16_f32 v29, v29, v29
	ds_write_b16 v177, v29 offset:60160
	v_fma_f32 v29, v143, v18, v215
	v_cvt_pk_bf16_f32 v29, v29, v29
	ds_write_b16 v178, v29 offset:60416
	v_fma_f32 v29, v141, v18, v215
	v_cvt_pk_bf16_f32 v29, v29, v29
	ds_write_b16 v179, v29 offset:60672
	v_fma_f32 v29, v139, v18, v215
	v_cvt_pk_bf16_f32 v29, v29, v29
	ds_write_b16 v182, v29 offset:60928
	v_fma_f32 v29, v137, v18, v215
	v_cvt_pk_bf16_f32 v29, v29, v29
	ds_write_b16 v183, v29 offset:61184
	v_fma_f32 v29, v144, v18, v215
	v_cvt_pk_bf16_f32 v29, v29, v29
	ds_write_b16 v184, v29 offset:61440
	v_fma_f32 v29, v142, v18, v215
	v_cvt_pk_bf16_f32 v29, v29, v29
	ds_write_b16 v185, v29 offset:61696
	v_fma_f32 v29, v140, v18, v215
	v_cvt_pk_bf16_f32 v29, v29, v29
	ds_write_b16 v186, v29 offset:61952
	v_fma_f32 v29, v138, v18, v215
	v_cvt_pk_bf16_f32 v29, v29, v29
	ds_write_b16 v187, v29 offset:62208
	v_fma_f32 v29, v133, v18, v215
	v_cvt_pk_bf16_f32 v29, v29, v29
	ds_write_b16 v188, v29 offset:62464
	v_fma_f32 v29, v131, v18, v215
	v_cvt_pk_bf16_f32 v29, v29, v29
	ds_write_b16 v189, v29 offset:62720
	v_fma_f32 v29, v64, v18, v215
	v_cvt_pk_bf16_f32 v29, v29, v29
	ds_write_b16 v190, v29 offset:62976
	v_fma_f32 v29, v62, v18, v215
	v_cvt_pk_bf16_f32 v29, v29, v29
	ds_write_b16 v35, v29 offset:63232
	v_fma_f32 v29, v136, v18, v215
	v_cvt_pk_bf16_f32 v29, v29, v29
	ds_write_b16 v174, v29 offset:63488
	v_fma_f32 v29, v132, v18, v215
	v_cvt_pk_bf16_f32 v29, v29, v29
	ds_write_b16 v175, v29 offset:63744
	v_fma_f32 v29, v65, v18, v215
	v_cvt_pk_bf16_f32 v29, v29, v29
	ds_write_b16 v176, v29 offset:64000
	v_fma_f32 v29, v63, v18, v215
	v_cvt_pk_bf16_f32 v29, v29, v29
	ds_write_b16 v177, v29 offset:64256
	v_fma_f32 v29, v60, v18, v215
	v_cvt_pk_bf16_f32 v29, v29, v29
	ds_write_b16 v178, v29 offset:64512
	v_fma_f32 v29, v59, v18, v215
	v_cvt_pk_bf16_f32 v29, v29, v29
	ds_write_b16 v179, v29 offset:64768
	v_fma_f32 v29, v57, v18, v215
	v_cvt_pk_bf16_f32 v29, v29, v29
	ds_write_b16 v182, v29 offset:65024
	v_fma_f32 v29, v55, v18, v215
	v_cvt_pk_bf16_f32 v29, v29, v29
	ds_write_b16 v183, v29 offset:65280
	v_fma_f32 v29, v61, v18, v215
	v_cvt_pk_bf16_f32 v29, v29, v29
	v_add3_u32 v35, v38, v168, v27
	ds_write_b16 v35, v29 offset:10240
	v_fma_f32 v29, v58, v18, v215
	v_cvt_pk_bf16_f32 v29, v29, v29
	v_add3_u32 v55, v38, v166, v27
	ds_write_b16 v55, v29 offset:10496
	v_fma_f32 v29, v56, v18, v215
	v_cvt_pk_bf16_f32 v29, v29, v29
	v_add3_u32 v56, v38, v164, v27
	ds_write_b16 v56, v29 offset:10752
	v_fma_f32 v29, v54, v18, v215
	v_cvt_pk_bf16_f32 v29, v29, v29
	v_add3_u32 v54, v38, v153, v27
	ds_write_b16 v54, v29 offset:11008
	v_fma_f32 v29, v53, v18, v215
	v_cvt_pk_bf16_f32 v29, v29, v29
	v_add3_u32 v53, v38, v152, v27
	ds_write_b16 v53, v29 offset:11264
	v_fma_f32 v29, v51, v18, v215
	v_cvt_pk_bf16_f32 v29, v29, v29
	v_add3_u32 v51, v38, v151, v27
	ds_write_b16 v51, v29 offset:11520
	v_fma_f32 v29, v49, v18, v215
	v_cvt_pk_bf16_f32 v29, v29, v29
	v_add3_u32 v49, v38, v148, v27
	ds_write_b16 v49, v29 offset:11776
	v_fma_f32 v29, v47, v18, v215
	v_cvt_pk_bf16_f32 v29, v29, v29
	v_add3_u32 v45, v38, v45, v27
	ds_write_b16 v45, v29 offset:12032
	v_fma_f32 v29, v52, v18, v215
	v_cvt_pk_bf16_f32 v29, v29, v29
	v_add3_u32 v46, v38, v46, v27
	ds_write_b16 v46, v29 offset:12288
	v_fma_f32 v29, v50, v18, v215
	v_cvt_pk_bf16_f32 v29, v29, v29
	v_add3_u32 v46, v38, v173, v27
	ds_write_b16 v46, v29 offset:12544
	v_fma_f32 v29, v48, v18, v215
	v_cvt_pk_bf16_f32 v29, v29, v29
	v_add3_u32 v46, v38, v172, v27
	ds_write_b16 v46, v29 offset:12800
	v_mul_f32_e32 v29, v37, v18
	v_bfe_u32 v36, v29, 16, 1
	v_add3_u32 v29, v29, v36, s15
	v_add3_u32 v36, v38, v171, v27
	ds_write_b16_d16_hi v36, v29 offset:13056
	v_fma_f32 v29, v34, v18, v215
	v_cvt_pk_bf16_f32 v29, v29, v29
	v_add3_u32 v34, v38, v170, v27
	ds_write_b16 v34, v29 offset:13312
	v_sub_f32_e32 v29, v24, v39
	v_pk_fma_f32 v[24:25], v[40:41], s[22:23], v[24:25] op_sel_hi:[1,0,1] neg_lo:[1,0,0] neg_hi:[1,0,0]
	v_mul_f32_e32 v29, v29, v18
	v_mul_f32_e32 v24, v25, v18
	v_bfe_u32 v34, v29, 16, 1
	v_bfe_u32 v25, v24, 16, 1
	v_add3_u32 v29, v29, v34, s15
	v_add3_u32 v34, v38, v169, v27
	v_add3_u32 v24, v24, v25, s15
	v_add3_u32 v25, v38, v167, v27
	ds_write_b16_d16_hi v34, v29 offset:13568
	ds_write_b16_d16_hi v25, v24 offset:13824
	v_pk_fma_f32 v[24:25], v[40:41], s[22:23], v[32:33] op_sel_hi:[1,0,1] neg_lo:[1,0,0] neg_hi:[1,0,0]
	v_and_b32_e32 v133, 15, v43
	v_mul_f32_e32 v24, v25, v18
	v_bfe_u32 v25, v24, 16, 1
	v_add3_u32 v24, v24, v25, s15
	v_add3_u32 v25, v38, v165, v27
	ds_write_b16_d16_hi v25, v24 offset:14080
	v_fma_f32 v24, v28, v18, v215
	v_cvt_pk_bf16_f32 v24, v24, v24
	ds_write_b16 v35, v24 offset:14336
	v_sub_f32_e32 v24, v22, v39
	v_pk_fma_f32 v[22:23], v[40:41], s[22:23], v[22:23] op_sel_hi:[1,0,1] neg_lo:[1,0,0] neg_hi:[1,0,0]
	v_mul_f32_e32 v24, v24, v18
	v_mul_f32_e32 v22, v23, v18
	v_bfe_u32 v25, v24, 16, 1
	v_bfe_u32 v23, v22, 16, 1
	v_add3_u32 v24, v24, v25, s15
	v_add3_u32 v22, v22, v23, s15
	ds_write_b16_d16_hi v55, v24 offset:14592
	ds_write_b16_d16_hi v56, v22 offset:14848
	v_pk_fma_f32 v[22:23], v[40:41], s[22:23], v[30:31] op_sel_hi:[1,0,1] neg_lo:[1,0,0] neg_hi:[1,0,0]
	s_nop 0
	v_mul_f32_e32 v22, v23, v18
	v_bfe_u32 v23, v22, 16, 1
	v_add3_u32 v22, v22, v23, s15
	ds_write_b16_d16_hi v54, v22 offset:15104
	v_fma_f32 v22, v26, v18, v215
	v_cvt_pk_bf16_f32 v22, v22, v22
	ds_write_b16 v53, v22 offset:15360
	v_sub_f32_e32 v22, v20, v39
	v_pk_fma_f32 v[20:21], v[40:41], s[22:23], v[20:21] op_sel_hi:[1,0,1] neg_lo:[1,0,0] neg_hi:[1,0,0]
	v_mul_f32_e32 v22, v22, v18
	v_mul_f32_e32 v20, v21, v18
	v_mul_f32_e32 v18, v19, v18
	v_bfe_u32 v23, v22, 16, 1
	v_bfe_u32 v21, v20, 16, 1
	v_bfe_u32 v19, v18, 16, 1
	v_add3_u32 v22, v22, v23, s15
	v_add3_u32 v20, v20, v21, s15
	v_add3_u32 v18, v18, v19, s15
	ds_write_b16_d16_hi v51, v22 offset:15616
	ds_write_b16_d16_hi v49, v20 offset:15872
	ds_write_b16_d16_hi v45, v18 offset:16128
	v_lshrrev_b32_e32 v18, 1, v43
	v_and_b32_e32 v18, 32, v18
	v_lshl_or_b32 v132, v44, 6, v18
	v_or_b32_e32 v18, v132, v134
	v_lshl_add_u32 v131, v18, 8, 32
	v_bitop3_b32 v18, v42, v133, 1 bitop3:0x6c
	v_lshl_add_u32 v18, v18, 4, v131
	s_waitcnt lgkmcnt(0)
	s_barrier
	ds_read_b128 v[136:139], v18 offset:55296
	s_waitcnt lgkmcnt(0)
	v_mfma_f32_32x32x16_bf16 v[50:65], v[136:139], v[2:5], 0
	v_mfma_f32_32x32x16_bf16 v[34:49], v[136:139], v[6:9], 0
	v_mfma_f32_32x32x16_bf16 v[18:33], v[136:139], v[10:13], 0
	v_mfma_f32_32x32x16_bf16 v[2:17], v[136:139], v[14:17], 0
	v_bitop3_b32 v136, v135, v133, 2 bitop3:0x36
	v_lshl_add_u32 v136, v136, 4, v131
	ds_read_b128 v[136:139], v136 offset:55296
	s_waitcnt lgkmcnt(0)
	v_mfma_f32_32x32x16_bf16 v[50:65], v[136:139], v[114:117], v[50:65]
	v_bitop3_b32 v114, v135, v133, 4 bitop3:0x36
	v_lshl_add_u32 v114, v114, 4, v131
	ds_read_b128 v[114:117], v114 offset:55296
	v_mfma_f32_32x32x16_bf16 v[34:49], v[136:139], v[118:121], v[34:49]
	v_mfma_f32_32x32x16_bf16 v[18:33], v[136:139], v[122:125], v[18:33]
	s_waitcnt lgkmcnt(0)
	v_mfma_f32_32x32x16_bf16 v[34:49], v[114:117], v[102:105], v[34:49]
	v_bitop3_b32 v102, v135, v133, 6 bitop3:0x36
	v_lshl_add_u32 v102, v102, 4, v131
	ds_read_b128 v[102:105], v102 offset:55296
	v_mfma_f32_32x32x16_bf16 v[2:17], v[136:139], v[126:129], v[2:17]
	v_mfma_f32_32x32x16_bf16 v[18:33], v[114:117], v[106:109], v[18:33]
	s_waitcnt lgkmcnt(0)
	v_mfma_f32_32x32x16_bf16 v[34:49], v[102:105], v[90:93], v[34:49]
	v_bitop3_b32 v90, v135, v133, 8 bitop3:0x36
	v_lshl_add_u32 v90, v90, 4, v131
	ds_read_b128 v[90:93], v90 offset:55296
	v_mfma_f32_32x32x16_bf16 v[2:17], v[114:117], v[110:113], v[2:17]
	v_mfma_f32_32x32x16_bf16 v[18:33], v[102:105], v[94:97], v[18:33]
	v_mfma_f32_32x32x16_bf16 v[2:17], v[102:105], v[98:101], v[2:17]
	v_lshlrev_b32_e32 v104, 7, v130
	v_or_b32_e32 v102, v104, v134
	v_ashrrev_i32_e32 v103, 31, v102
	v_lshlrev_b64 v[106:107], 2, v[102:103]
	v_lshl_or_b32 v98, v135, 2, v132
	v_or_b32_e32 v100, s3, v134
	v_mov_b32_e32 v101, s5
	s_waitcnt lgkmcnt(0)
	v_mfma_f32_32x32x16_bf16 v[18:33], v[90:93], v[82:85], v[18:33]
	v_bitop3_b32 v82, v135, v133, 10 bitop3:0x36
	v_lshl_add_u32 v82, v82, 4, v131
	ds_read_b128 v[82:85], v82 offset:55296
	v_lshl_add_u64 v[108:109], s[6:7], 0, v[106:107]
	v_lshl_add_u64 v[106:107], s[92:93], 0, v[106:107]
	v_ashrrev_i32_e32 v99, 31, v98
	v_lshlrev_b64 v[98:99], 1, v[98:99]
	v_mfma_f32_32x32x16_bf16 v[2:17], v[90:93], v[86:89], v[2:17]
	s_add_i32 s3, s3, s18
	s_cmpk_gt_i32 s4, 0x7f
	s_waitcnt lgkmcnt(0)
	v_mfma_f32_32x32x16_bf16 v[18:33], v[82:85], v[74:77], v[18:33]
	v_bitop3_b32 v74, v135, v133, 12 bitop3:0x36
	v_lshl_add_u32 v74, v74, 4, v131
	ds_read_b128 v[74:77], v74 offset:55296
	v_mfma_f32_32x32x16_bf16 v[2:17], v[82:85], v[78:81], v[2:17]
	s_waitcnt lgkmcnt(0)
	v_mfma_f32_32x32x16_bf16 v[2:17], v[74:77], v[70:73], v[2:17]
	v_bitop3_b32 v70, v135, v133, 14 bitop3:0x36
	v_lshl_add_u32 v70, v70, 4, v131
	ds_read_b128 v[70:73], v70 offset:55296
	v_ashrrev_i32_e32 v133, 31, v132
	s_waitcnt lgkmcnt(0)
	v_mfma_f32_32x32x16_bf16 v[2:17], v[70:73], v[66:69], v[2:17]
	v_lshlrev_b64 v[66:67], 2, v[132:133]
	v_lshl_add_u64 v[68:69], s[10:11], 0, v[66:67]
	v_lshl_add_u64 v[66:67], s[36:37], 0, v[66:67]
	v_lshl_add_u64 v[68:69], v[68:69], 0, v[154:155]
	v_lshl_add_u64 v[70:71], v[66:67], 0, v[154:155]
	global_load_dwordx4 v[90:93], v[68:69], off
	global_load_dwordx4 v[94:97], v[70:71], off
	global_load_dwordx4 v[82:85], v[68:69], off offset:32
	global_load_dwordx4 v[86:89], v[70:71], off offset:32
	global_load_dwordx4 v[74:77], v[68:69], off offset:64
	global_load_dwordx4 v[78:81], v[70:71], off offset:64
	s_nop 0
	global_load_dwordx4 v[66:69], v[68:69], off offset:96
	s_nop 0
	global_load_dwordx4 v[70:73], v[70:71], off offset:96
	s_nop 0
	global_load_dword v150, v[108:109], off
	global_load_dword v151, v[108:109], off offset:128
	global_load_dword v152, v[108:109], off offset:256
	global_load_dword v153, v[108:109], off offset:384
	global_load_dword v164, v[106:107], off
	global_load_dword v165, v[106:107], off offset:128
	global_load_dword v166, v[106:107], off offset:256
	global_load_dword v167, v[106:107], off offset:384
	v_lshlrev_b64 v[142:143], 11, v[100:101]
	v_lshl_add_u64 v[142:143], s[62:63], 0, v[142:143]
	v_lshl_add_u64 v[142:143], v[142:143], 0, v[98:99]
	v_bfe_u32 v169, v0, 5, 1
	v_lshlrev_b32_e32 v169, 3, v169
	v_add_co_u32_e32 v142, vcc, v142, v169
	s_nop 1
	v_addc_co_u32_e32 v143, vcc, 0, v143, vcc
	v_add_co_u32_e32 v144, vcc, 0x10000, v142
	s_nop 1
	v_addc_co_u32_e32 v145, vcc, 0, v143, vcc
	v_add_co_u32_e32 v146, vcc, 0x20000, v142
	s_nop 1
	v_addc_co_u32_e32 v147, vcc, 0, v143, vcc
	v_add_co_u32_e32 v148, vcc, 0x30000, v142
	s_nop 1
	v_addc_co_u32_e32 v149, vcc, 0, v143, vcc
	s_waitcnt vmcnt(0)
	v_mul_f32_e32 v168, v94, v150
	v_fmac_f32_e32 v168, v50, v90
	v_add_f32_e32 v50, v164, v168
	v_lshlrev_b32_e32 v169, 16, v216
	v_mul_f32_e32 v50, v50, v169
	v_mul_f32_e32 v168, v95, v150
	v_fmac_f32_e32 v168, v51, v91
	v_add_f32_e32 v51, v164, v168
	v_and_b32_e32 v169, 0xffff0000, v216
	v_mul_f32_e32 v51, v51, v169
	v_mul_f32_e32 v168, v96, v150
	v_fmac_f32_e32 v168, v52, v92
	v_add_f32_e32 v52, v164, v168
	v_lshlrev_b32_e32 v169, 16, v217
	v_mul_f32_e32 v52, v52, v169
	v_mul_f32_e32 v168, v97, v150
	v_fmac_f32_e32 v168, v53, v93
	v_add_f32_e32 v53, v164, v168
	v_and_b32_e32 v169, 0xffff0000, v217
	v_mul_f32_e32 v53, v53, v169
	v_cvt_pk_bf16_f32 v50, v50, v51
	v_cvt_pk_bf16_f32 v51, v52, v53
	v_mul_f32_e32 v168, v86, v150
	v_fmac_f32_e32 v168, v54, v82
	v_add_f32_e32 v54, v164, v168
	v_lshlrev_b32_e32 v169, 16, v218
	v_mul_f32_e32 v54, v54, v169
	v_mul_f32_e32 v168, v87, v150
	v_fmac_f32_e32 v168, v55, v83
	v_add_f32_e32 v55, v164, v168
	v_and_b32_e32 v169, 0xffff0000, v218
	v_mul_f32_e32 v55, v55, v169
	v_mul_f32_e32 v168, v88, v150
	v_fmac_f32_e32 v168, v56, v84
	v_add_f32_e32 v56, v164, v168
	v_lshlrev_b32_e32 v169, 16, v219
	v_mul_f32_e32 v56, v56, v169
	v_mul_f32_e32 v168, v89, v150
	v_fmac_f32_e32 v168, v57, v85
	v_add_f32_e32 v57, v164, v168
	v_and_b32_e32 v169, 0xffff0000, v219
	v_mul_f32_e32 v57, v57, v169
	v_cvt_pk_bf16_f32 v52, v54, v55
	v_cvt_pk_bf16_f32 v53, v56, v57
	s_nop 1
	v_permlane32_swap_b32 v50, v52
	v_permlane32_swap_b32 v51, v53
	global_store_dwordx4 v[142:143], v[50:53], off offset:1536
	v_mul_f32_e32 v168, v78, v150
	v_fmac_f32_e32 v168, v58, v74
	v_add_f32_e32 v58, v164, v168
	v_lshlrev_b32_e32 v169, 16, v220
	v_mul_f32_e32 v58, v58, v169
	v_mul_f32_e32 v168, v79, v150
	v_fmac_f32_e32 v168, v59, v75
	v_add_f32_e32 v59, v164, v168
	v_and_b32_e32 v169, 0xffff0000, v220
	v_mul_f32_e32 v59, v59, v169
	v_mul_f32_e32 v168, v80, v150
	v_fmac_f32_e32 v168, v60, v76
	v_add_f32_e32 v60, v164, v168
	v_lshlrev_b32_e32 v169, 16, v221
	v_mul_f32_e32 v60, v60, v169
	v_mul_f32_e32 v168, v81, v150
	v_fmac_f32_e32 v168, v61, v77
	v_add_f32_e32 v61, v164, v168
	v_and_b32_e32 v169, 0xffff0000, v221
	v_mul_f32_e32 v61, v61, v169
	v_cvt_pk_bf16_f32 v58, v58, v59
	v_cvt_pk_bf16_f32 v59, v60, v61
	v_mul_f32_e32 v168, v70, v150
	v_fmac_f32_e32 v168, v62, v66
	v_add_f32_e32 v62, v164, v168
	v_lshlrev_b32_e32 v169, 16, v222
	v_mul_f32_e32 v62, v62, v169
	v_mul_f32_e32 v168, v71, v150
	v_fmac_f32_e32 v168, v63, v67
	v_add_f32_e32 v63, v164, v168
	v_and_b32_e32 v169, 0xffff0000, v222
	v_mul_f32_e32 v63, v63, v169
	v_mul_f32_e32 v168, v72, v150
	v_fmac_f32_e32 v168, v64, v68
	v_add_f32_e32 v64, v164, v168
	v_lshlrev_b32_e32 v169, 16, v223
	v_mul_f32_e32 v64, v64, v169
	v_mul_f32_e32 v168, v73, v150
	v_fmac_f32_e32 v168, v65, v69
	v_add_f32_e32 v65, v164, v168
	v_and_b32_e32 v169, 0xffff0000, v223
	v_mul_f32_e32 v65, v65, v169
	v_cvt_pk_bf16_f32 v60, v62, v63
	v_cvt_pk_bf16_f32 v61, v64, v65
	s_nop 1
	v_permlane32_swap_b32 v58, v60
	v_permlane32_swap_b32 v59, v61
	global_store_dwordx4 v[142:143], v[58:61], off offset:1568
	v_mul_f32_e32 v168, v94, v151
	v_fmac_f32_e32 v168, v34, v90
	v_add_f32_e32 v34, v165, v168
	v_lshlrev_b32_e32 v169, 16, v224
	v_mul_f32_e32 v34, v34, v169
	v_mul_f32_e32 v168, v95, v151
	v_fmac_f32_e32 v168, v35, v91
	v_add_f32_e32 v35, v165, v168
	v_and_b32_e32 v169, 0xffff0000, v224
	v_mul_f32_e32 v35, v35, v169
	v_mul_f32_e32 v168, v96, v151
	v_fmac_f32_e32 v168, v36, v92
	v_add_f32_e32 v36, v165, v168
	v_lshlrev_b32_e32 v169, 16, v225
	v_mul_f32_e32 v36, v36, v169
	v_mul_f32_e32 v168, v97, v151
	v_fmac_f32_e32 v168, v37, v93
	v_add_f32_e32 v37, v165, v168
	v_and_b32_e32 v169, 0xffff0000, v225
	v_mul_f32_e32 v37, v37, v169
	v_cvt_pk_bf16_f32 v34, v34, v35
	v_cvt_pk_bf16_f32 v35, v36, v37
	v_mul_f32_e32 v168, v86, v151
	v_fmac_f32_e32 v168, v38, v82
	v_add_f32_e32 v38, v165, v168
	v_lshlrev_b32_e32 v169, 16, v226
	v_mul_f32_e32 v38, v38, v169
	v_mul_f32_e32 v168, v87, v151
	v_fmac_f32_e32 v168, v39, v83
	v_add_f32_e32 v39, v165, v168
	v_and_b32_e32 v169, 0xffff0000, v226
	v_mul_f32_e32 v39, v39, v169
	v_mul_f32_e32 v168, v88, v151
	v_fmac_f32_e32 v168, v40, v84
	v_add_f32_e32 v40, v165, v168
	v_lshlrev_b32_e32 v169, 16, v227
	v_mul_f32_e32 v40, v40, v169
	v_mul_f32_e32 v168, v89, v151
	v_fmac_f32_e32 v168, v41, v85
	v_add_f32_e32 v41, v165, v168
	v_and_b32_e32 v169, 0xffff0000, v227
	v_mul_f32_e32 v41, v41, v169
	v_cvt_pk_bf16_f32 v36, v38, v39
	v_cvt_pk_bf16_f32 v37, v40, v41
	s_nop 1
	v_permlane32_swap_b32 v34, v36
	v_permlane32_swap_b32 v35, v37
	global_store_dwordx4 v[144:145], v[34:37], off offset:1536
	v_mul_f32_e32 v168, v78, v151
	v_fmac_f32_e32 v168, v42, v74
	v_add_f32_e32 v42, v165, v168
	v_lshlrev_b32_e32 v169, 16, v228
	v_mul_f32_e32 v42, v42, v169
	v_mul_f32_e32 v168, v79, v151
	v_fmac_f32_e32 v168, v43, v75
	v_add_f32_e32 v43, v165, v168
	v_and_b32_e32 v169, 0xffff0000, v228
	v_mul_f32_e32 v43, v43, v169
	v_mul_f32_e32 v168, v80, v151
	v_fmac_f32_e32 v168, v44, v76
	v_add_f32_e32 v44, v165, v168
	v_lshlrev_b32_e32 v169, 16, v229
	v_mul_f32_e32 v44, v44, v169
	v_mul_f32_e32 v168, v81, v151
	v_fmac_f32_e32 v168, v45, v77
	v_add_f32_e32 v45, v165, v168
	v_and_b32_e32 v169, 0xffff0000, v229
	v_mul_f32_e32 v45, v45, v169
	v_cvt_pk_bf16_f32 v42, v42, v43
	v_cvt_pk_bf16_f32 v43, v44, v45
	v_mul_f32_e32 v168, v70, v151
	v_fmac_f32_e32 v168, v46, v66
	v_add_f32_e32 v46, v165, v168
	v_lshlrev_b32_e32 v169, 16, v230
	v_mul_f32_e32 v46, v46, v169
	v_mul_f32_e32 v168, v71, v151
	v_fmac_f32_e32 v168, v47, v67
	v_add_f32_e32 v47, v165, v168
	v_and_b32_e32 v169, 0xffff0000, v230
	v_mul_f32_e32 v47, v47, v169
	v_mul_f32_e32 v168, v72, v151
	v_fmac_f32_e32 v168, v48, v68
	v_add_f32_e32 v48, v165, v168
	v_lshlrev_b32_e32 v169, 16, v231
	v_mul_f32_e32 v48, v48, v169
	v_mul_f32_e32 v168, v73, v151
	v_fmac_f32_e32 v168, v49, v69
	v_add_f32_e32 v49, v165, v168
	v_and_b32_e32 v169, 0xffff0000, v231
	v_mul_f32_e32 v49, v49, v169
	v_cvt_pk_bf16_f32 v44, v46, v47
	v_cvt_pk_bf16_f32 v45, v48, v49
	s_nop 1
	v_permlane32_swap_b32 v42, v44
	v_permlane32_swap_b32 v43, v45
	global_store_dwordx4 v[144:145], v[42:45], off offset:1568
	v_mul_f32_e32 v168, v94, v152
	v_fmac_f32_e32 v168, v18, v90
	v_add_f32_e32 v18, v166, v168
	v_lshlrev_b32_e32 v169, 16, v232
	v_mul_f32_e32 v18, v18, v169
	v_mul_f32_e32 v168, v95, v152
	v_fmac_f32_e32 v168, v19, v91
	v_add_f32_e32 v19, v166, v168
	v_and_b32_e32 v169, 0xffff0000, v232
	v_mul_f32_e32 v19, v19, v169
	v_mul_f32_e32 v168, v96, v152
	v_fmac_f32_e32 v168, v20, v92
	v_add_f32_e32 v20, v166, v168
	v_lshlrev_b32_e32 v169, 16, v233
	v_mul_f32_e32 v20, v20, v169
	v_mul_f32_e32 v168, v97, v152
	v_fmac_f32_e32 v168, v21, v93
	v_add_f32_e32 v21, v166, v168
	v_and_b32_e32 v169, 0xffff0000, v233
	v_mul_f32_e32 v21, v21, v169
	v_cvt_pk_bf16_f32 v18, v18, v19
	v_cvt_pk_bf16_f32 v19, v20, v21
	v_mul_f32_e32 v168, v86, v152
	v_fmac_f32_e32 v168, v22, v82
	v_add_f32_e32 v22, v166, v168
	v_lshlrev_b32_e32 v169, 16, v234
	v_mul_f32_e32 v22, v22, v169
	v_mul_f32_e32 v168, v87, v152
	v_fmac_f32_e32 v168, v23, v83
	v_add_f32_e32 v23, v166, v168
	v_and_b32_e32 v169, 0xffff0000, v234
	v_mul_f32_e32 v23, v23, v169
	v_mul_f32_e32 v168, v88, v152
	v_fmac_f32_e32 v168, v24, v84
	v_add_f32_e32 v24, v166, v168
	v_lshlrev_b32_e32 v169, 16, v235
	v_mul_f32_e32 v24, v24, v169
	v_mul_f32_e32 v168, v89, v152
	v_fmac_f32_e32 v168, v25, v85
	v_add_f32_e32 v25, v166, v168
	v_and_b32_e32 v169, 0xffff0000, v235
	v_mul_f32_e32 v25, v25, v169
	v_cvt_pk_bf16_f32 v20, v22, v23
	v_cvt_pk_bf16_f32 v21, v24, v25
	s_nop 1
	v_permlane32_swap_b32 v18, v20
	v_permlane32_swap_b32 v19, v21
	global_store_dwordx4 v[146:147], v[18:21], off offset:1536
	v_mul_f32_e32 v168, v78, v152
	v_fmac_f32_e32 v168, v26, v74
	v_add_f32_e32 v26, v166, v168
	v_lshlrev_b32_e32 v169, 16, v236
	v_mul_f32_e32 v26, v26, v169
	v_mul_f32_e32 v168, v79, v152
	v_fmac_f32_e32 v168, v27, v75
	v_add_f32_e32 v27, v166, v168
	v_and_b32_e32 v169, 0xffff0000, v236
	v_mul_f32_e32 v27, v27, v169
	v_mul_f32_e32 v168, v80, v152
	v_fmac_f32_e32 v168, v28, v76
	v_add_f32_e32 v28, v166, v168
	v_lshlrev_b32_e32 v169, 16, v237
	v_mul_f32_e32 v28, v28, v169
	v_mul_f32_e32 v168, v81, v152
	v_fmac_f32_e32 v168, v29, v77
	v_add_f32_e32 v29, v166, v168
	v_and_b32_e32 v169, 0xffff0000, v237
	v_mul_f32_e32 v29, v29, v169
	v_cvt_pk_bf16_f32 v26, v26, v27
	v_cvt_pk_bf16_f32 v27, v28, v29
	v_mul_f32_e32 v168, v70, v152
	v_fmac_f32_e32 v168, v30, v66
	v_add_f32_e32 v30, v166, v168
	v_lshlrev_b32_e32 v169, 16, v238
	v_mul_f32_e32 v30, v30, v169
	v_mul_f32_e32 v168, v71, v152
	v_fmac_f32_e32 v168, v31, v67
	v_add_f32_e32 v31, v166, v168
	v_and_b32_e32 v169, 0xffff0000, v238
	v_mul_f32_e32 v31, v31, v169
	v_mul_f32_e32 v168, v72, v152
	v_fmac_f32_e32 v168, v32, v68
	v_add_f32_e32 v32, v166, v168
	v_lshlrev_b32_e32 v169, 16, v239
	v_mul_f32_e32 v32, v32, v169
	v_mul_f32_e32 v168, v73, v152
	v_fmac_f32_e32 v168, v33, v69
	v_add_f32_e32 v33, v166, v168
	v_and_b32_e32 v169, 0xffff0000, v239
	v_mul_f32_e32 v33, v33, v169
	v_cvt_pk_bf16_f32 v28, v30, v31
	v_cvt_pk_bf16_f32 v29, v32, v33
	s_nop 1
	v_permlane32_swap_b32 v26, v28
	v_permlane32_swap_b32 v27, v29
	global_store_dwordx4 v[146:147], v[26:29], off offset:1568
	v_mul_f32_e32 v168, v94, v153
	v_fmac_f32_e32 v168, v2, v90
	v_add_f32_e32 v2, v167, v168
	v_lshlrev_b32_e32 v169, 16, v240
	v_mul_f32_e32 v2, v2, v169
	v_mul_f32_e32 v168, v95, v153
	v_fmac_f32_e32 v168, v3, v91
	v_add_f32_e32 v3, v167, v168
	v_and_b32_e32 v169, 0xffff0000, v240
	v_mul_f32_e32 v3, v3, v169
	v_mul_f32_e32 v168, v96, v153
	v_fmac_f32_e32 v168, v4, v92
	v_add_f32_e32 v4, v167, v168
	v_lshlrev_b32_e32 v169, 16, v241
	v_mul_f32_e32 v4, v4, v169
	v_mul_f32_e32 v168, v97, v153
	v_fmac_f32_e32 v168, v5, v93
	v_add_f32_e32 v5, v167, v168
	v_and_b32_e32 v169, 0xffff0000, v241
	v_mul_f32_e32 v5, v5, v169
	v_cvt_pk_bf16_f32 v2, v2, v3
	v_cvt_pk_bf16_f32 v3, v4, v5
	v_mul_f32_e32 v168, v86, v153
	v_fmac_f32_e32 v168, v6, v82
	v_add_f32_e32 v6, v167, v168
	v_lshlrev_b32_e32 v169, 16, v246
	v_mul_f32_e32 v6, v6, v169
	v_mul_f32_e32 v168, v87, v153
	v_fmac_f32_e32 v168, v7, v83
	v_add_f32_e32 v7, v167, v168
	v_and_b32_e32 v169, 0xffff0000, v246
	v_mul_f32_e32 v7, v7, v169
	v_mul_f32_e32 v168, v88, v153
	v_fmac_f32_e32 v168, v8, v84
	v_add_f32_e32 v8, v167, v168
	v_lshlrev_b32_e32 v169, 16, v247
	v_mul_f32_e32 v8, v8, v169
	v_mul_f32_e32 v168, v89, v153
	v_fmac_f32_e32 v168, v9, v85
	v_add_f32_e32 v9, v167, v168
	v_and_b32_e32 v169, 0xffff0000, v247
	v_mul_f32_e32 v9, v9, v169
	v_cvt_pk_bf16_f32 v4, v6, v7
	v_cvt_pk_bf16_f32 v5, v8, v9
	s_nop 1
	v_permlane32_swap_b32 v2, v4
	v_permlane32_swap_b32 v3, v5
	global_store_dwordx4 v[148:149], v[2:5], off offset:1536
	v_mul_f32_e32 v168, v78, v153
	v_fmac_f32_e32 v168, v10, v74
	v_add_f32_e32 v10, v167, v168
	v_lshlrev_b32_e32 v169, 16, v252
	v_mul_f32_e32 v10, v10, v169
	v_mul_f32_e32 v168, v79, v153
	v_fmac_f32_e32 v168, v11, v75
	v_add_f32_e32 v11, v167, v168
	v_and_b32_e32 v169, 0xffff0000, v252
	v_mul_f32_e32 v11, v11, v169
	v_mul_f32_e32 v168, v80, v153
	v_fmac_f32_e32 v168, v12, v76
	v_add_f32_e32 v12, v167, v168
	v_lshlrev_b32_e32 v169, 16, v253
	v_mul_f32_e32 v12, v12, v169
	v_mul_f32_e32 v168, v81, v153
	v_fmac_f32_e32 v168, v13, v77
	v_add_f32_e32 v13, v167, v168
	v_and_b32_e32 v169, 0xffff0000, v253
	v_mul_f32_e32 v13, v13, v169
	v_cvt_pk_bf16_f32 v10, v10, v11
	v_cvt_pk_bf16_f32 v11, v12, v13
	v_mul_f32_e32 v168, v70, v153
	v_fmac_f32_e32 v168, v14, v66
	v_add_f32_e32 v14, v167, v168
	v_lshlrev_b32_e32 v169, 16, v254
	v_mul_f32_e32 v14, v14, v169
	v_mul_f32_e32 v168, v71, v153
	v_fmac_f32_e32 v168, v15, v67
	v_add_f32_e32 v15, v167, v168
	v_and_b32_e32 v169, 0xffff0000, v254
	v_mul_f32_e32 v15, v15, v169
	v_mul_f32_e32 v168, v72, v153
	v_fmac_f32_e32 v168, v16, v68
	v_add_f32_e32 v16, v167, v168
	v_lshlrev_b32_e32 v169, 16, v255
	v_mul_f32_e32 v16, v16, v169
	v_mul_f32_e32 v168, v73, v153
	v_fmac_f32_e32 v168, v17, v69
	v_add_f32_e32 v17, v167, v168
	v_and_b32_e32 v169, 0xffff0000, v255
	v_mul_f32_e32 v17, v17, v169
	v_cvt_pk_bf16_f32 v12, v14, v15
	v_cvt_pk_bf16_f32 v13, v16, v17
	s_nop 1
	v_permlane32_swap_b32 v10, v12
	v_permlane32_swap_b32 v11, v13
	global_store_dwordx4 v[148:149], v[10:13], off offset:1568
	s_barrier
	s_cbranch_scc0 .LBB0_849
